# PEER q+topk item: the eight sub-key row loads for LDS staging issued together before the barrier with counted waits (was eight serialized load-wait-write steps, twice per item)
# speedup vs baseline: 1.0052x; 1.0052x over previous
; DEV f32x16 mfma32(bf16x8 a, bf16x8 b, f32x16 c) { return __builtin_amdgcn_mfma_f32_32x32x16_bf16(a, b, c, 0, 0, 0); }
; DEV void gemm_core(const bf16_t* __restrict__ A, const bf16_t* __restrict__ Bt, int m0, int n0, bf16_t* As, bf16_t* Bs, int tid,
;                    f32x16 (&acc)[2][2]) {
;     ...
;   GLOAD(0);
;   for (int kt = 0; kt < 16; ++kt) {
;     __syncthreads();
;     {
;       bf16_t* as = As + lrow * 72 + lc8; bf16_t* bs = Bs + lrow * 72 + lc8;
;       *(uint4*)(as) = ra0; *(uint4*)(as + 32 * 72) = ra1; *(uint4*)(as + 64 * 72) = ra2; *(uint4*)(as + 96 * 72) = ra3;
;       *(uint4*)(bs) = rb0; *(uint4*)(bs + 32 * 72) = rb1; *(uint4*)(bs + 64 * 72) = rb2; *(uint4*)(bs + 96 * 72) = rb3;
;     }
;     __syncthreads();
;     {
;       const int k0 = (kt + 1 < 16) ? (kt + 1) * 64 : 15 * 64;
;       GLOAD(k0);
;     }
; #pragma unroll
;     for (int kk = 0; kk < 4; ++kk) {
;       bf16x8 af[2], bfr[2];
; #pragma unroll
;       for (int mi = 0; mi < 2; ++mi) af[mi] = *(const bf16x8*)(As + (wm * 64 + mi * 32 + lr) * 72 + kk * 16 + hk * 8);
; #pragma unroll
;       for (int ni = 0; ni < 2; ++ni) bfr[ni] = *(const bf16x8*)(Bs + (wn * 64 + ni * 32 + lr) * 72 + kk * 16 + hk * 8);
; #pragma unroll
;       for (int mi = 0; mi < 2; ++mi)
; #pragma unroll
;         for (int ni = 0; ni < 2; ++ni) acc[mi][ni] = mfma32(af[mi], bfr[ni], acc[mi][ni]);
;     }
.LBB0_46:
	s_barrier
	s_waitcnt vmcnt(6)
	ds_write_b128 v98, v[68:71]
	s_waitcnt vmcnt(5)
	ds_write_b128 v98, v[72:75] offset:4608
	s_waitcnt vmcnt(4)
	ds_write_b128 v98, v[76:79] offset:9216
	s_waitcnt vmcnt(3)
	ds_write_b128 v98, v[80:83] offset:13824
	s_waitcnt vmcnt(3)
	ds_write_b128 v98, v[64:67] offset:18432
	s_waitcnt vmcnt(2)
	ds_write_b128 v98, v[84:87] offset:23040
	s_waitcnt vmcnt(1)
	ds_write_b128 v98, v[88:91] offset:27648
	s_waitcnt vmcnt(0)
	ds_write_b128 v98, v[92:95] offset:32256
	s_waitcnt lgkmcnt(0)
	s_barrier
	ds_read_b128 v[64:67], v189
	ds_read_b128 v[68:71], v190 offset:18432
	ds_read_b128 v[72:75], v189 offset:32
	ds_read_b128 v[76:79], v190 offset:18464
	ds_read_b128 v[80:83], v190 offset:23040
	ds_read_b128 v[84:87], v190 offset:23072
	s_waitcnt lgkmcnt(4)
	v_mfma_f32_32x32x16_bf16 v[48:63], v[64:67], v[68:71], v[48:63]
	s_waitcnt lgkmcnt(1)
	v_mfma_f32_32x32x16_bf16 v[32:47], v[64:67], v[80:83], v[32:47]
	ds_read_b128 v[64:67], v189 offset:4608
	ds_read_b128 v[88:91], v189 offset:4640
	s_waitcnt lgkmcnt(1)
	v_mfma_f32_32x32x16_bf16 v[16:31], v[64:67], v[68:71], v[16:31]
	v_mfma_f32_32x32x16_bf16 v[48:63], v[72:75], v[76:79], v[48:63]
	v_mfma_f32_32x32x16_bf16 v[32:47], v[72:75], v[84:87], v[32:47]
	v_mfma_f32_32x32x16_bf16 v[0:15], v[64:67], v[80:83], v[0:15]
	ds_read_b128 v[64:67], v189 offset:64
	ds_read_b128 v[68:71], v190 offset:18496
	ds_read_b128 v[72:75], v189 offset:96
	ds_read_b128 v[92:95], v190 offset:18528
	v_lshl_add_u64 v[80:81], v[148:149], 0, s[38:39]
	v_lshl_add_u64 v[82:83], v[150:151], 0, s[38:39]
	s_add_u32 s38, s38, 0x80
	s_addc_u32 s39, s39, 0
	s_cmpk_lg_i32 s38, 0x780
	s_waitcnt lgkmcnt(4)
	v_mfma_f32_32x32x16_bf16 v[16:31], v[88:91], v[76:79], v[16:31]
	ds_read_b128 v[76:79], v190 offset:23104
	ds_read_b128 v[192:195], v190 offset:23136
	ds_read_b128 v[196:199], v189 offset:4704
	s_waitcnt lgkmcnt(5)
	v_mfma_f32_32x32x16_bf16 v[48:63], v[64:67], v[68:71], v[48:63]
	s_waitcnt lgkmcnt(2)
	v_mfma_f32_32x32x16_bf16 v[32:47], v[64:67], v[76:79], v[32:47]
	ds_read_b128 v[64:67], v189 offset:4672
	v_mfma_f32_32x32x16_bf16 v[0:15], v[88:91], v[84:87], v[0:15]
	v_add_co_u32_e32 v84, vcc, s42, v80
	s_nop 1
	v_addc_co_u32_e32 v85, vcc, 0, v81, vcc
	v_add_co_u32_e32 v86, vcc, s43, v80
	s_waitcnt lgkmcnt(0)
	v_mfma_f32_32x32x16_bf16 v[16:31], v[64:67], v[68:71], v[16:31]
	v_addc_co_u32_e32 v87, vcc, 0, v81, vcc
	v_add_co_u32_e32 v88, vcc, s44, v80
	s_nop 1
	v_addc_co_u32_e32 v89, vcc, 0, v81, vcc
	v_add_co_u32_e32 v90, vcc, s42, v82
	v_mfma_f32_32x32x16_bf16 v[0:15], v[64:67], v[76:79], v[0:15]
	s_nop 0
	v_addc_co_u32_e32 v91, vcc, 0, v83, vcc
	v_add_co_u32_e32 v200, vcc, s43, v82
	global_load_dwordx4 v[64:67], v[82:83], off offset:128
	s_nop 0
	v_addc_co_u32_e32 v201, vcc, 0, v83, vcc
	v_add_co_u32_e32 v228, vcc, s44, v82
	v_mfma_f32_32x32x16_bf16 v[48:63], v[72:75], v[92:95], v[48:63]
	s_nop 0
	v_addc_co_u32_e32 v229, vcc, 0, v83, vcc
	v_mfma_f32_32x32x16_bf16 v[32:47], v[72:75], v[192:195], v[32:47]
	global_load_dwordx4 v[68:71], v[80:81], off offset:128
	global_load_dwordx4 v[72:75], v[84:85], off offset:128
	global_load_dwordx4 v[76:79], v[86:87], off offset:128
	s_nop 0
	global_load_dwordx4 v[80:83], v[88:89], off offset:128
	global_load_dwordx4 v[84:87], v[90:91], off offset:128
	s_nop 0
	global_load_dwordx4 v[88:91], v[200:201], off offset:128
	v_mfma_f32_32x32x16_bf16 v[16:31], v[196:199], v[92:95], v[16:31]
	global_load_dwordx4 v[92:95], v[228:229], off offset:128
	v_mfma_f32_32x32x16_bf16 v[0:15], v[196:199], v[192:195], v[0:15]
	s_cbranch_scc1 .LBB0_46
	s_barrier
	s_waitcnt vmcnt(6)
	ds_write_b128 v98, v[68:71]
	s_waitcnt vmcnt(5)
	ds_write_b128 v98, v[72:75] offset:4608
	s_waitcnt vmcnt(4)
	ds_write_b128 v98, v[76:79] offset:9216
	s_waitcnt vmcnt(3)
	ds_write_b128 v98, v[80:83] offset:13824
	ds_write_b128 v98, v[64:67] offset:18432
	s_waitcnt vmcnt(2)
	ds_write_b128 v98, v[84:87] offset:23040
	s_waitcnt vmcnt(1)
	ds_write_b128 v98, v[88:91] offset:27648
	s_waitcnt vmcnt(0)
	ds_write_b128 v98, v[92:95] offset:32256
	s_waitcnt lgkmcnt(0)
	s_barrier
	ds_read_b128 v[64:67], v189 offset:4608
	ds_read_b128 v[68:71], v190 offset:23040
	ds_read_b128 v[72:75], v189
	ds_read_b128 v[76:79], v189 offset:32
	ds_read_b128 v[80:83], v190 offset:18432
	ds_read_b128 v[84:87], v190 offset:18464
	s_waitcnt lgkmcnt(1)
	v_mfma_f32_32x32x16_bf16 v[48:63], v[72:75], v[80:83], v[48:63]
	v_readlane_b32 s38, v249, 58
	s_or_b32 s38, s41, s38
	s_ashr_i32 s39, s38, 31
	s_lshl_b64 s[38:39], s[38:39], 8
	s_movk_i32 s41, 0x80
	v_mfma_f32_32x32x16_bf16 v[32:47], v[72:75], v[68:71], v[32:47]
	v_mfma_f32_32x32x16_bf16 v[16:31], v[64:67], v[80:83], v[16:31]
	v_mfma_f32_32x32x16_bf16 v[0:15], v[64:67], v[68:71], v[0:15]
	ds_read_b128 v[64:67], v189 offset:4640
	ds_read_b128 v[68:71], v190 offset:23072
	s_waitcnt lgkmcnt(2)
	v_mfma_f32_32x32x16_bf16 v[48:63], v[76:79], v[84:87], v[48:63]
	s_waitcnt lgkmcnt(0)
	v_mfma_f32_32x32x16_bf16 v[32:47], v[76:79], v[68:71], v[32:47]
	v_mfma_f32_32x32x16_bf16 v[16:31], v[64:67], v[84:87], v[16:31]
	v_mfma_f32_32x32x16_bf16 v[0:15], v[64:67], v[68:71], v[0:15]
	ds_read_b128 v[64:67], v189 offset:64
	ds_read_b128 v[68:71], v189 offset:4672
	ds_read_b128 v[72:75], v190 offset:18496
	ds_read_b128 v[76:79], v190 offset:23104
	s_waitcnt lgkmcnt(1)
	v_mfma_f32_32x32x16_bf16 v[48:63], v[64:67], v[72:75], v[48:63]
	s_waitcnt lgkmcnt(0)
	v_mfma_f32_32x32x16_bf16 v[32:47], v[64:67], v[76:79], v[32:47]
	v_mfma_f32_32x32x16_bf16 v[16:31], v[68:71], v[72:75], v[16:31]
	v_mfma_f32_32x32x16_bf16 v[0:15], v[68:71], v[76:79], v[0:15]
	ds_read_b128 v[64:67], v189 offset:96
	ds_read_b128 v[68:71], v189 offset:4704
	ds_read_b128 v[72:75], v190 offset:18528
	ds_read_b128 v[76:79], v190 offset:23136
	s_waitcnt lgkmcnt(1)
; DEV unsigned short f2bf(float f) { return (unsigned short)(pack2(f, 0.f) & 0xFFFFu); }
; __device__ void peer_q_topk_item(const Params& P, int l, int item, char* smem) {
;     ...
; #pragma unroll
;       for (int mi = 0; mi < 2; ++mi)
; #pragma unroll
;         for (int ni = 0; ni < 2; ++ni) {
;           const int col = wn * 64 + ni * 32 + lr;
;           const int rbase = wm * 64 + mi * 32 + 4 * hk;
; #pragma unroll
;           for (int i = 0; i < 16; ++i) Qs[(rbase + (i & 3) + 8 * (i >> 2)) * 136 + col] = f2bf(acc[mi][ni][i]);
;         }
;     }
;     __syncthreads();
;     {
;       const bf16_t* skg = P.SK + (size_t)((l * 2 + c) * 128) * 128;
; #pragma unroll
;       for (int k = 0; k < 8; ++k) {
;         const int ch = tid + 256 * k;
;         const int row = ch >> 4, c8 = (ch & 15) * 8;
;         *(uint4*)(As + row * 136 + c8) = *(const uint4*)(skg + row * 128 + c8);
;       }
;     }
	v_mfma_f32_32x32x16_bf16 v[48:63], v[64:67], v[72:75], v[48:63]
	s_waitcnt lgkmcnt(0)
	v_mfma_f32_32x32x16_bf16 v[32:47], v[64:67], v[76:79], v[32:47]
	s_nop 9
	v_cvt_pk_bf16_f32 v48, v48, s0
	ds_write_b16 v102, v48 offset:36864
	v_cvt_pk_bf16_f32 v48, v49, s0
	ds_write_b16 v183, v48 offset:36864
	v_cvt_pk_bf16_f32 v48, v50, s0
	ds_write_b16 v184, v48 offset:36864
	v_cvt_pk_bf16_f32 v48, v51, s0
	ds_write_b16 v185, v48 offset:36864
	v_cvt_pk_bf16_f32 v48, v52, s0
	ds_write_b16 v186, v48 offset:36864
	v_cvt_pk_bf16_f32 v48, v53, s0
	ds_write_b16 v102, v48 offset:39312
	v_cvt_pk_bf16_f32 v48, v54, s0
	ds_write_b16 v102, v48 offset:39584
	v_cvt_pk_bf16_f32 v48, v55, s0
	ds_write_b16 v102, v48 offset:39856
	v_cvt_pk_bf16_f32 v48, v56, s0
	ds_write_b16 v187, v48 offset:36864
	v_cvt_pk_bf16_f32 v48, v57, s0
	ds_write_b16 v102, v48 offset:41488
	v_cvt_pk_bf16_f32 v48, v58, s0
	ds_write_b16 v102, v48 offset:41760
	v_cvt_pk_bf16_f32 v48, v59, s0
	ds_write_b16 v102, v48 offset:42032
	v_cvt_pk_bf16_f32 v48, v60, s0
	ds_write_b16 v188, v48 offset:36864
	v_cvt_pk_bf16_f32 v48, v61, s0
	ds_write_b16 v102, v48 offset:43664
	v_cvt_pk_bf16_f32 v48, v62, s0
	v_cvt_pk_bf16_f32 v32, v32, s0
	ds_write_b16 v102, v48 offset:43936
	v_cvt_pk_bf16_f32 v48, v63, s0
	ds_write_b16 v102, v32 offset:36928
	v_cvt_pk_bf16_f32 v32, v33, s0
	ds_write_b16 v102, v48 offset:44208
	ds_write_b16 v183, v32 offset:36928
	v_cvt_pk_bf16_f32 v32, v34, s0
	ds_write_b16 v184, v32 offset:36928
	v_cvt_pk_bf16_f32 v32, v35, s0
	v_mfma_f32_32x32x16_bf16 v[0:15], v[68:71], v[76:79], v[0:15]
	ds_write_b16 v185, v32 offset:36928
	v_cvt_pk_bf16_f32 v32, v36, s0
	ds_write_b16 v186, v32 offset:36928
	v_cvt_pk_bf16_f32 v32, v37, s0
	ds_write_b16 v102, v32 offset:39376
	v_cvt_pk_bf16_f32 v32, v38, s0
	ds_write_b16 v102, v32 offset:39648
	v_mfma_f32_32x32x16_bf16 v[16:31], v[68:71], v[72:75], v[16:31]
	v_cvt_pk_bf16_f32 v32, v39, s0
	ds_write_b16 v102, v32 offset:39920
	v_cvt_pk_bf16_f32 v32, v40, s0
	ds_write_b16 v187, v32 offset:36928
	v_cvt_pk_bf16_f32 v32, v41, s0
	ds_write_b16 v102, v32 offset:41552
	v_cvt_pk_bf16_f32 v32, v42, s0
	ds_write_b16 v102, v32 offset:41824
	v_cvt_pk_bf16_f32 v32, v43, s0
	ds_write_b16 v102, v32 offset:42096
	v_cvt_pk_bf16_f32 v32, v44, s0
	v_cvt_pk_bf16_f32 v0, v0, s0
	ds_write_b16 v188, v32 offset:36928
	v_cvt_pk_bf16_f32 v16, v16, s0
	ds_write_b16 v102, v0 offset:45632
	v_cvt_pk_bf16_f32 v0, v1, s0
	ds_write_b16 v102, v16 offset:45568
	v_cvt_pk_bf16_f32 v16, v17, s0
	ds_write_b16 v102, v0 offset:45904
	v_cvt_pk_bf16_f32 v0, v2, s0
	ds_write_b16 v102, v16 offset:45840
	v_cvt_pk_bf16_f32 v16, v18, s0
	ds_write_b16 v102, v0 offset:46176
	v_cvt_pk_bf16_f32 v0, v3, s0
	ds_write_b16 v102, v16 offset:46112
	v_cvt_pk_bf16_f32 v16, v19, s0
	ds_write_b16 v102, v0 offset:46448
	v_cvt_pk_bf16_f32 v0, v4, s0
	ds_write_b16 v102, v16 offset:46384
	v_cvt_pk_bf16_f32 v16, v20, s0
	ds_write_b16 v102, v0 offset:47808
	v_cvt_pk_bf16_f32 v0, v5, s0
	ds_write_b16 v102, v16 offset:47744
	v_cvt_pk_bf16_f32 v16, v21, s0
	ds_write_b16 v102, v0 offset:48080
	v_cvt_pk_bf16_f32 v0, v6, s0
	ds_write_b16 v102, v16 offset:48016
	v_cvt_pk_bf16_f32 v16, v22, s0
	ds_write_b16 v102, v0 offset:48352
	v_cvt_pk_bf16_f32 v0, v7, s0
	ds_write_b16 v102, v16 offset:48288
	v_cvt_pk_bf16_f32 v16, v23, s0
	ds_write_b16 v102, v0 offset:48624
	v_cvt_pk_bf16_f32 v0, v8, s0
	ds_write_b16 v102, v16 offset:48560
	v_cvt_pk_bf16_f32 v16, v24, s0
	ds_write_b16 v102, v0 offset:49984
	v_cvt_pk_bf16_f32 v0, v9, s0
	ds_write_b16 v102, v16 offset:49920
	v_cvt_pk_bf16_f32 v16, v25, s0
	ds_write_b16 v102, v0 offset:50256
	v_cvt_pk_bf16_f32 v0, v10, s0
	ds_write_b16 v102, v16 offset:50192
	v_cvt_pk_bf16_f32 v16, v26, s0
	ds_write_b16 v102, v0 offset:50528
	v_cvt_pk_bf16_f32 v0, v11, s0
	ds_write_b16 v102, v16 offset:50464
	v_cvt_pk_bf16_f32 v16, v27, s0
	ds_write_b16 v102, v0 offset:50800
	v_cvt_pk_bf16_f32 v0, v12, s0
	ds_write_b16 v102, v16 offset:50736
	v_cvt_pk_bf16_f32 v16, v28, s0
	ds_write_b16 v102, v0 offset:52160
	v_cvt_pk_bf16_f32 v0, v13, s0
	v_cvt_pk_bf16_f32 v32, v45, s0
	ds_write_b16 v102, v16 offset:52096
	v_cvt_pk_bf16_f32 v16, v29, s0
	ds_write_b16 v102, v0 offset:52432
	v_cvt_pk_bf16_f32 v0, v14, s0
	ds_write_b16 v102, v32 offset:43728
	v_cvt_pk_bf16_f32 v32, v46, s0
	ds_write_b16 v102, v16 offset:52368
	v_cvt_pk_bf16_f32 v16, v30, s0
	ds_write_b16 v102, v0 offset:52704
	v_cvt_pk_bf16_f32 v0, v15, s0
	v_lshl_add_u64 v[4:5], v[146:147], 0, s[38:39]
	ds_write_b16 v102, v32 offset:44000
	v_cvt_pk_bf16_f32 v32, v47, s0
	ds_write_b16 v102, v16 offset:52640
	v_cvt_pk_bf16_f32 v16, v31, s0
	ds_write_b16 v102, v0 offset:52976
	v_lshl_add_u64 v[0:1], v[104:105], 1, v[4:5]
	ds_write_b16 v102, v32 offset:44272
	ds_write_b16 v102, v16 offset:52912
	global_load_dwordx4 v[64:67], v[0:1], off
	v_lshl_add_u64 v[0:1], v[108:109], 1, v[4:5]
	global_load_dwordx4 v[68:71], v[0:1], off
	v_lshl_add_u64 v[0:1], v[112:113], 1, v[4:5]
	global_load_dwordx4 v[72:75], v[0:1], off
	v_lshl_add_u64 v[0:1], v[116:117], 1, v[4:5]
	global_load_dwordx4 v[76:79], v[0:1], off
	v_lshl_add_u64 v[0:1], v[120:121], 1, v[4:5]
	global_load_dwordx4 v[80:83], v[0:1], off
	v_lshl_add_u64 v[0:1], v[124:125], 1, v[4:5]
	global_load_dwordx4 v[84:87], v[0:1], off
	v_lshl_add_u64 v[0:1], v[128:129], 1, v[4:5]
	global_load_dwordx4 v[88:91], v[0:1], off
	v_lshl_add_u64 v[0:1], v[132:133], 1, v[4:5]
	global_load_dwordx4 v[92:95], v[0:1], off
	s_waitcnt lgkmcnt(0)
	s_barrier
; DEV f32x16 mfma32(bf16x8 a, bf16x8 b, f32x16 c) { return __builtin_amdgcn_mfma_f32_32x32x16_bf16(a, b, c, 0, 0, 0); }
; __device__ void peer_q_topk_item(const Params& P, int l, int item, char* smem) {
;     ...
;     __syncthreads();
;     {
;       const bf16_t* skg = P.SK + (size_t)((l * 2 + c) * 128) * 128;
; #pragma unroll
;       for (int k = 0; k < 8; ++k) {
;         const int ch = tid + 256 * k;
;         const int row = ch >> 4, c8 = (ch & 15) * 8;
;         *(uint4*)(As + row * 136 + c8) = *(const uint4*)(skg + row * 128 + c8);
;       }
;     }
;     __syncthreads();
;     unsigned Lc[16];
;     {
;       f32x16 sa[4];
; #pragma unroll
;       for (int m4 = 0; m4 < 4; ++m4)
; #pragma unroll
;         for (int i = 0; i < 16; ++i) sa[m4][i] = 0.f;
;       const bf16_t* qrow = Qs + (w * 32 + q) * 136 + hk * 8;
;       const bf16_t* sk = As + q * 136 + hk * 8;
; #pragma unroll
;       for (int ks = 0; ks < 8; ++ks) {
;         const bf16x8 bq = *(const bf16x8*)(qrow + ks * 16);
; #pragma unroll
;         for (int m4 = 0; m4 < 4; ++m4) {
;           const bf16x8 a = *(const bf16x8*)(sk + (m4 * 32) * 136 + ks * 16);
;           sa[m4] = mfma32(a, bq, sa[m4]);
;         }
;       }
	s_movk_i32 s39, 0x7f
	s_movk_i32 s38, 0x5f
	s_waitcnt vmcnt(7)
	ds_write_b128 v106, v[64:67]
	s_waitcnt vmcnt(6)
	ds_write_b128 v110, v[68:71]
	s_waitcnt vmcnt(5)
	ds_write_b128 v114, v[72:75]
	s_waitcnt vmcnt(4)
	ds_write_b128 v118, v[76:79]
	s_waitcnt vmcnt(3)
	ds_write_b128 v122, v[80:83]
	s_waitcnt vmcnt(2)
	ds_write_b128 v126, v[84:87]
	s_waitcnt vmcnt(1)
	ds_write_b128 v130, v[88:91]
	s_waitcnt vmcnt(0)
	ds_write_b128 v134, v[92:95]
	s_waitcnt lgkmcnt(0)
	s_barrier
	ds_read_b128 v[0:3], v100 offset:36864
	ds_read_b128 v[64:67], v100 offset:36896
	ds_read_b128 v[4:7], v160
	ds_read_b128 v[68:71], v160 offset:32
	s_waitcnt lgkmcnt(1)
	v_mfma_f32_32x32x16_bf16 v[48:63], v[4:7], v[0:3], 0
	ds_read_b128 v[4:7], v160 offset:8704
	s_waitcnt lgkmcnt(1)
	v_mfma_f32_32x32x16_bf16 v[48:63], v[68:71], v[64:67], v[48:63]
	ds_read_b128 v[68:71], v160 offset:8736
	s_waitcnt lgkmcnt(1)
	v_mfma_f32_32x32x16_bf16 v[32:47], v[4:7], v[0:3], 0
	ds_read_b128 v[4:7], v160 offset:17408
	s_waitcnt lgkmcnt(1)
	v_mfma_f32_32x32x16_bf16 v[32:47], v[68:71], v[64:67], v[32:47]
	ds_read_b128 v[68:71], v160 offset:17440
	s_waitcnt lgkmcnt(1)
	v_mfma_f32_32x32x16_bf16 v[16:31], v[4:7], v[0:3], 0
	ds_read_b128 v[4:7], v160 offset:26112
	s_waitcnt lgkmcnt(1)
	v_mfma_f32_32x32x16_bf16 v[16:31], v[68:71], v[64:67], v[16:31]
	ds_read_b128 v[68:71], v160 offset:26144
	s_waitcnt lgkmcnt(1)
	v_mfma_f32_32x32x16_bf16 v[0:15], v[4:7], v[0:3], 0
	s_waitcnt lgkmcnt(0)
	v_mfma_f32_32x32x16_bf16 v[0:15], v[68:71], v[64:67], v[0:15]
	ds_read_b128 v[64:67], v100 offset:36928
	ds_read_b128 v[68:71], v160 offset:64
	s_waitcnt lgkmcnt(0)
	v_mfma_f32_32x32x16_bf16 v[48:63], v[68:71], v[64:67], v[48:63]
	ds_read_b128 v[68:71], v160 offset:8768
	s_waitcnt lgkmcnt(0)
	v_mfma_f32_32x32x16_bf16 v[32:47], v[68:71], v[64:67], v[32:47]
	ds_read_b128 v[68:71], v160 offset:17472
	s_waitcnt lgkmcnt(0)
	v_mfma_f32_32x32x16_bf16 v[16:31], v[68:71], v[64:67], v[16:31]
	ds_read_b128 v[68:71], v160 offset:26176
	s_waitcnt lgkmcnt(0)
	v_mfma_f32_32x32x16_bf16 v[0:15], v[68:71], v[64:67], v[0:15]
	ds_read_b128 v[64:67], v100 offset:36960
	ds_read_b128 v[68:71], v160 offset:96
	s_waitcnt lgkmcnt(0)
	v_mfma_f32_32x32x16_bf16 v[48:63], v[68:71], v[64:67], v[48:63]
	ds_read_b128 v[68:71], v160 offset:8800
	s_waitcnt lgkmcnt(0)
	v_mfma_f32_32x32x16_bf16 v[32:47], v[68:71], v[64:67], v[32:47]
	ds_read_b128 v[68:71], v160 offset:17504
	s_waitcnt lgkmcnt(0)
	v_mfma_f32_32x32x16_bf16 v[16:31], v[68:71], v[64:67], v[16:31]
	ds_read_b128 v[68:71], v160 offset:26208
	s_waitcnt lgkmcnt(0)
	v_mfma_f32_32x32x16_bf16 v[0:15], v[68:71], v[64:67], v[0:15]
	ds_read_b128 v[64:67], v100 offset:36992
	ds_read_b128 v[68:71], v160 offset:128
	s_waitcnt lgkmcnt(0)
	v_mfma_f32_32x32x16_bf16 v[48:63], v[68:71], v[64:67], v[48:63]
	ds_read_b128 v[68:71], v160 offset:8832
	s_waitcnt lgkmcnt(0)
	v_mfma_f32_32x32x16_bf16 v[32:47], v[68:71], v[64:67], v[32:47]
	ds_read_b128 v[68:71], v160 offset:17536
	s_waitcnt lgkmcnt(0)
	v_mfma_f32_32x32x16_bf16 v[16:31], v[68:71], v[64:67], v[16:31]
	ds_read_b128 v[68:71], v160 offset:26240
	s_waitcnt lgkmcnt(0)
	v_mfma_f32_32x32x16_bf16 v[0:15], v[68:71], v[64:67], v[0:15]
	ds_read_b128 v[64:67], v100 offset:37024
	ds_read_b128 v[68:71], v160 offset:160
	s_waitcnt lgkmcnt(0)
	v_mfma_f32_32x32x16_bf16 v[48:63], v[68:71], v[64:67], v[48:63]
	ds_read_b128 v[68:71], v160 offset:8864
	s_waitcnt lgkmcnt(0)
	v_mfma_f32_32x32x16_bf16 v[32:47], v[68:71], v[64:67], v[32:47]
	ds_read_b128 v[68:71], v160 offset:17568
	s_waitcnt lgkmcnt(0)
	v_mfma_f32_32x32x16_bf16 v[16:31], v[68:71], v[64:67], v[16:31]
	ds_read_b128 v[68:71], v160 offset:26272
	s_waitcnt lgkmcnt(0)
	v_mfma_f32_32x32x16_bf16 v[0:15], v[68:71], v[64:67], v[0:15]
	ds_read_b128 v[64:67], v100 offset:37056
	ds_read_b128 v[68:71], v160 offset:192
	s_waitcnt lgkmcnt(0)
	v_mfma_f32_32x32x16_bf16 v[48:63], v[68:71], v[64:67], v[48:63]
	ds_read_b128 v[68:71], v160 offset:8896
	s_waitcnt lgkmcnt(0)
	v_mfma_f32_32x32x16_bf16 v[32:47], v[68:71], v[64:67], v[32:47]
	ds_read_b128 v[68:71], v160 offset:17600
	s_waitcnt lgkmcnt(0)
	v_mfma_f32_32x32x16_bf16 v[16:31], v[68:71], v[64:67], v[16:31]
	ds_read_b128 v[68:71], v160 offset:26304
	s_waitcnt lgkmcnt(0)
	v_mfma_f32_32x32x16_bf16 v[0:15], v[68:71], v[64:67], v[0:15]
	ds_read_b128 v[64:67], v100 offset:37088
	ds_read_b128 v[68:71], v160 offset:224
	s_waitcnt lgkmcnt(0)
	v_mfma_f32_32x32x16_bf16 v[48:63], v[68:71], v[64:67], v[48:63]
	ds_read_b128 v[68:71], v160 offset:8928
	s_waitcnt lgkmcnt(0)
	v_mfma_f32_32x32x16_bf16 v[32:47], v[68:71], v[64:67], v[32:47]
	ds_read_b128 v[68:71], v160 offset:17632
	s_nop 7
	v_cmp_gt_i32_e32 vcc, 0, v48
	s_waitcnt lgkmcnt(0)
	v_mfma_f32_32x32x16_bf16 v[16:31], v[68:71], v[64:67], v[16:31]
	ds_read_b128 v[68:71], v160 offset:26336
	s_waitcnt lgkmcnt(0)
; DEV unsigned fkey(float v) { const unsigned u = __float_as_uint(v); return (u & 0x80000000u) ? ~u : (u | 0x80000000u); }
; __device__ void peer_q_topk_item(const Params& P, int l, int item, char* smem) {
;     ...
;       unsigned G1[16], G2[16], G3[16];
; #pragma unroll
;       for (int i = 0; i < 16; ++i) {
;         const int kb0 = (i & 3) + 8 * (i >> 2) + 4 * hk;
;         Lc[i] = (fkey(sa[0][i]) & ~0x7Fu) | (unsigned)(127 - kb0);
;         G1[i] = (fkey(sa[1][i]) & ~0x7Fu) | (unsigned)(127 - (32 + kb0));
;         G2[i] = (fkey(sa[2][i]) & ~0x7Fu) | (unsigned)(127 - (64 + kb0));
;         G3[i] = (fkey(sa[3][i]) & ~0x7Fu) | (unsigned)(127 - (96 + kb0));
;       }
	v_mfma_f32_32x32x16_bf16 v[0:15], v[68:71], v[64:67], v[0:15]
	v_not_b32_e32 v64, v48
	v_or_b32_e32 v65, 0x80000000, v48
	v_cndmask_b32_e32 v48, v65, v64, vcc
	v_not_b32_e32 v64, v32
	v_or_b32_e32 v65, 0x80000000, v32
	v_cmp_gt_i32_e32 vcc, 0, v32
	v_and_b32_e32 v48, 0xffffff80, v48
	v_bitop3_b32 v48, v48, s39, v159 bitop3:0x36
	v_cndmask_b32_e32 v32, v65, v64, vcc
	v_not_b32_e32 v64, v16
	v_or_b32_e32 v65, 0x80000000, v16
	v_cmp_gt_i32_e32 vcc, 0, v16
	v_and_b32_e32 v32, 0xffffff80, v32
	v_bitop3_b32 v32, v32, s38, v159 bitop3:0x36
	v_cndmask_b32_e32 v16, v65, v64, vcc
	v_not_b32_e32 v64, v0
	v_or_b32_e32 v65, 0x80000000, v0
	v_cmp_gt_i32_e32 vcc, 0, v0
	v_and_b32_e32 v16, 0xffffff80, v16
	v_bitop3_b32 v16, v16, 63, v159 bitop3:0x36
	v_cndmask_b32_e32 v0, v65, v64, vcc
	v_not_b32_e32 v64, v49
	v_or_b32_e32 v65, 0x80000000, v49
	v_cmp_gt_i32_e32 vcc, 0, v49
	v_and_b32_e32 v0, 0xffffff80, v0
	v_bitop3_b32 v0, v0, 31, v159 bitop3:0x36
	v_cndmask_b32_e32 v49, v65, v64, vcc
	v_not_b32_e32 v64, v33
	v_or_b32_e32 v65, 0x80000000, v33
	v_cmp_gt_i32_e32 vcc, 0, v33
	v_and_b32_e32 v49, 0xffffff80, v49
	v_bitop3_b32 v49, v49, s39, v163 bitop3:0x36
	v_cndmask_b32_e32 v33, v65, v64, vcc
	v_not_b32_e32 v64, v17
	v_or_b32_e32 v65, 0x80000000, v17
	v_cmp_gt_i32_e32 vcc, 0, v17
	v_and_b32_e32 v33, 0xffffff80, v33
	v_bitop3_b32 v33, v33, s38, v163 bitop3:0x36
	v_cndmask_b32_e32 v17, v65, v64, vcc
	v_not_b32_e32 v64, v1
	v_or_b32_e32 v65, 0x80000000, v1
	v_cmp_gt_i32_e32 vcc, 0, v1
	v_and_b32_e32 v17, 0xffffff80, v17
	v_bitop3_b32 v17, v17, 63, v163 bitop3:0x36
	v_cndmask_b32_e32 v1, v65, v64, vcc
	v_not_b32_e32 v64, v50
	v_or_b32_e32 v65, 0x80000000, v50
	v_cmp_gt_i32_e32 vcc, 0, v50
	v_and_b32_e32 v1, 0xffffff80, v1
	v_bitop3_b32 v1, v1, 31, v163 bitop3:0x36
	v_cndmask_b32_e32 v50, v65, v64, vcc
	v_not_b32_e32 v64, v34
	v_or_b32_e32 v65, 0x80000000, v34
	v_cmp_gt_i32_e32 vcc, 0, v34
	v_and_b32_e32 v50, 0xffffff80, v50
	v_bitop3_b32 v50, v50, s39, v164 bitop3:0x36
	v_cndmask_b32_e32 v34, v65, v64, vcc
	v_not_b32_e32 v64, v18
	v_or_b32_e32 v65, 0x80000000, v18
	v_cmp_gt_i32_e32 vcc, 0, v18
	v_and_b32_e32 v34, 0xffffff80, v34
	v_bitop3_b32 v34, v34, s38, v164 bitop3:0x36
	v_cndmask_b32_e32 v18, v65, v64, vcc
	v_not_b32_e32 v64, v2
	v_or_b32_e32 v65, 0x80000000, v2
	v_cmp_gt_i32_e32 vcc, 0, v2
	v_and_b32_e32 v18, 0xffffff80, v18
	v_bitop3_b32 v18, v18, 63, v164 bitop3:0x36
	v_cndmask_b32_e32 v2, v65, v64, vcc
	v_not_b32_e32 v64, v51
	v_or_b32_e32 v65, 0x80000000, v51
	v_cmp_gt_i32_e32 vcc, 0, v51
	v_and_b32_e32 v2, 0xffffff80, v2
	v_bitop3_b32 v2, v2, 31, v164 bitop3:0x36
	v_cndmask_b32_e32 v51, v65, v64, vcc
	v_not_b32_e32 v64, v35
	v_or_b32_e32 v65, 0x80000000, v35
	v_cmp_gt_i32_e32 vcc, 0, v35
	v_and_b32_e32 v51, 0xffffff80, v51
	v_bitop3_b32 v51, v51, s39, v166 bitop3:0x36
	v_cndmask_b32_e32 v35, v65, v64, vcc
	v_not_b32_e32 v64, v19
	v_or_b32_e32 v65, 0x80000000, v19
	v_cmp_gt_i32_e32 vcc, 0, v19
	v_and_b32_e32 v35, 0xffffff80, v35
	v_bitop3_b32 v35, v35, s38, v166 bitop3:0x36
	v_cndmask_b32_e32 v19, v65, v64, vcc
	v_not_b32_e32 v64, v3
	v_or_b32_e32 v65, 0x80000000, v3
	v_cmp_gt_i32_e32 vcc, 0, v3
	v_and_b32_e32 v19, 0xffffff80, v19
	v_bitop3_b32 v19, v19, 63, v166 bitop3:0x36
	v_cndmask_b32_e32 v3, v65, v64, vcc
	v_not_b32_e32 v64, v52
	v_or_b32_e32 v65, 0x80000000, v52
	v_cmp_gt_i32_e32 vcc, 0, v52
	v_and_b32_e32 v3, 0xffffff80, v3
	v_bitop3_b32 v3, v3, 31, v166 bitop3:0x36
	v_cndmask_b32_e32 v52, v65, v64, vcc
	v_not_b32_e32 v64, v36
	v_or_b32_e32 v65, 0x80000000, v36
	v_cmp_gt_i32_e32 vcc, 0, v36
	v_and_b32_e32 v52, 0xffffff80, v52
	v_bitop3_b32 v52, v52, s39, v167 bitop3:0x36
	v_cndmask_b32_e32 v36, v65, v64, vcc
	v_not_b32_e32 v64, v20
	v_or_b32_e32 v65, 0x80000000, v20
	v_cmp_gt_i32_e32 vcc, 0, v20
	v_and_b32_e32 v36, 0xffffff80, v36
	v_bitop3_b32 v36, v36, s38, v167 bitop3:0x36
	v_cndmask_b32_e32 v20, v65, v64, vcc
	v_not_b32_e32 v64, v4
	v_or_b32_e32 v65, 0x80000000, v4
	v_cmp_gt_i32_e32 vcc, 0, v4
	v_and_b32_e32 v20, 0xffffff80, v20
	v_bitop3_b32 v20, v20, 63, v167 bitop3:0x36
	v_cndmask_b32_e32 v4, v65, v64, vcc
	v_not_b32_e32 v64, v53
	v_or_b32_e32 v65, 0x80000000, v53
	v_cmp_gt_i32_e32 vcc, 0, v53
	v_and_b32_e32 v4, 0xffffff80, v4
	v_bitop3_b32 v4, v4, 31, v167 bitop3:0x36
	v_cndmask_b32_e32 v53, v65, v64, vcc
	v_not_b32_e32 v64, v37
	v_or_b32_e32 v65, 0x80000000, v37
	v_cmp_gt_i32_e32 vcc, 0, v37
	v_and_b32_e32 v53, 0xffffff80, v53
	v_bitop3_b32 v53, v53, s39, v171 bitop3:0x36
	v_cndmask_b32_e32 v37, v65, v64, vcc
	v_not_b32_e32 v64, v21
	v_or_b32_e32 v65, 0x80000000, v21
	v_cmp_gt_i32_e32 vcc, 0, v21
	v_and_b32_e32 v37, 0xffffff80, v37
	v_bitop3_b32 v37, v37, s38, v171 bitop3:0x36
	v_cndmask_b32_e32 v21, v65, v64, vcc
	v_not_b32_e32 v64, v5
	v_or_b32_e32 v65, 0x80000000, v5
	v_cmp_gt_i32_e32 vcc, 0, v5
	v_and_b32_e32 v21, 0xffffff80, v21
	v_bitop3_b32 v21, v21, 63, v171 bitop3:0x36
	v_cndmask_b32_e32 v5, v65, v64, vcc
	v_not_b32_e32 v64, v54
	v_or_b32_e32 v65, 0x80000000, v54
	v_cmp_gt_i32_e32 vcc, 0, v54
	v_and_b32_e32 v5, 0xffffff80, v5
	v_bitop3_b32 v5, v5, 31, v171 bitop3:0x36
	v_cndmask_b32_e32 v54, v65, v64, vcc
	v_not_b32_e32 v64, v38
	v_or_b32_e32 v65, 0x80000000, v38
	v_cmp_gt_i32_e32 vcc, 0, v38
	v_and_b32_e32 v54, 0xffffff80, v54
	v_bitop3_b32 v54, v54, s39, v172 bitop3:0x36
	v_cndmask_b32_e32 v38, v65, v64, vcc
	v_not_b32_e32 v64, v22
	v_or_b32_e32 v65, 0x80000000, v22
	v_cmp_gt_i32_e32 vcc, 0, v22
	v_and_b32_e32 v38, 0xffffff80, v38
	v_bitop3_b32 v38, v38, s38, v172 bitop3:0x36
	v_cndmask_b32_e32 v22, v65, v64, vcc
	v_not_b32_e32 v64, v6
	v_or_b32_e32 v65, 0x80000000, v6
	v_cmp_gt_i32_e32 vcc, 0, v6
	v_and_b32_e32 v22, 0xffffff80, v22
; DEV unsigned fkey(float v) { const unsigned u = __float_as_uint(v); return (u & 0x80000000u) ? ~u : (u | 0x80000000u); }
; __device__ void peer_q_topk_item(const Params& P, int l, int item, char* smem) {
;     ...
;       unsigned G1[16], G2[16], G3[16];
; #pragma unroll
;       for (int i = 0; i < 16; ++i) {
;         const int kb0 = (i & 3) + 8 * (i >> 2) + 4 * hk;
;         Lc[i] = (fkey(sa[0][i]) & ~0x7Fu) | (unsigned)(127 - kb0);
;         G1[i] = (fkey(sa[1][i]) & ~0x7Fu) | (unsigned)(127 - (32 + kb0));
;         G2[i] = (fkey(sa[2][i]) & ~0x7Fu) | (unsigned)(127 - (64 + kb0));
;         G3[i] = (fkey(sa[3][i]) & ~0x7Fu) | (unsigned)(127 - (96 + kb0));
;       }
	v_bitop3_b32 v22, v22, 63, v172 bitop3:0x36
	v_cndmask_b32_e32 v6, v65, v64, vcc
	v_not_b32_e32 v64, v55
	v_or_b32_e32 v65, 0x80000000, v55
	v_cmp_gt_i32_e32 vcc, 0, v55
	v_and_b32_e32 v6, 0xffffff80, v6
	v_bitop3_b32 v6, v6, 31, v172 bitop3:0x36
	v_cndmask_b32_e32 v55, v65, v64, vcc
	v_not_b32_e32 v64, v39
	v_or_b32_e32 v65, 0x80000000, v39
	v_cmp_gt_i32_e32 vcc, 0, v39
	v_and_b32_e32 v55, 0xffffff80, v55
	v_bitop3_b32 v55, v55, s39, v173 bitop3:0x36
	v_cndmask_b32_e32 v39, v65, v64, vcc
	v_not_b32_e32 v64, v23
	v_or_b32_e32 v65, 0x80000000, v23
	v_cmp_gt_i32_e32 vcc, 0, v23
	v_and_b32_e32 v39, 0xffffff80, v39
	v_bitop3_b32 v39, v39, s38, v173 bitop3:0x36
	v_cndmask_b32_e32 v23, v65, v64, vcc
	v_not_b32_e32 v64, v7
	v_or_b32_e32 v65, 0x80000000, v7
	v_cmp_gt_i32_e32 vcc, 0, v7
	v_and_b32_e32 v23, 0xffffff80, v23
	v_bitop3_b32 v23, v23, 63, v173 bitop3:0x36
	v_cndmask_b32_e32 v7, v65, v64, vcc
	v_not_b32_e32 v64, v56
	v_or_b32_e32 v65, 0x80000000, v56
	v_cmp_gt_i32_e32 vcc, 0, v56
	v_and_b32_e32 v7, 0xffffff80, v7
	v_bitop3_b32 v7, v7, 31, v173 bitop3:0x36
	v_cndmask_b32_e32 v56, v65, v64, vcc
	v_not_b32_e32 v64, v40
	v_or_b32_e32 v65, 0x80000000, v40
	v_cmp_gt_i32_e32 vcc, 0, v40
	v_and_b32_e32 v56, 0xffffff80, v56
	v_bitop3_b32 v56, v56, s39, v169 bitop3:0x36
	v_cndmask_b32_e32 v40, v65, v64, vcc
	v_not_b32_e32 v64, v24
	v_or_b32_e32 v65, 0x80000000, v24
	v_cmp_gt_i32_e32 vcc, 0, v24
	v_and_b32_e32 v40, 0xffffff80, v40
	v_bitop3_b32 v40, v40, s38, v169 bitop3:0x36
	v_cndmask_b32_e32 v24, v65, v64, vcc
	v_not_b32_e32 v64, v8
	v_or_b32_e32 v65, 0x80000000, v8
	v_cmp_gt_i32_e32 vcc, 0, v8
	v_and_b32_e32 v24, 0xffffff80, v24
	v_bitop3_b32 v24, v24, 63, v169 bitop3:0x36
	v_cndmask_b32_e32 v8, v65, v64, vcc
	v_not_b32_e32 v64, v57
	v_or_b32_e32 v65, 0x80000000, v57
	v_cmp_gt_i32_e32 vcc, 0, v57
	v_and_b32_e32 v8, 0xffffff80, v8
	v_bitop3_b32 v8, v8, 31, v169 bitop3:0x36
	v_cndmask_b32_e32 v57, v65, v64, vcc
	v_not_b32_e32 v64, v41
	v_or_b32_e32 v65, 0x80000000, v41
	v_cmp_gt_i32_e32 vcc, 0, v41
	v_and_b32_e32 v57, 0xffffff80, v57
	v_bitop3_b32 v57, v57, s39, v174 bitop3:0x36
	v_cndmask_b32_e32 v41, v65, v64, vcc
	v_not_b32_e32 v64, v25
	v_or_b32_e32 v65, 0x80000000, v25
	v_cmp_gt_i32_e32 vcc, 0, v25
	v_and_b32_e32 v41, 0xffffff80, v41
	v_bitop3_b32 v41, v41, s38, v174 bitop3:0x36
	v_cndmask_b32_e32 v25, v65, v64, vcc
	v_not_b32_e32 v64, v9
	v_or_b32_e32 v65, 0x80000000, v9
	v_cmp_gt_i32_e32 vcc, 0, v9
	v_and_b32_e32 v25, 0xffffff80, v25
	v_bitop3_b32 v25, v25, 63, v174 bitop3:0x36
	v_cndmask_b32_e32 v9, v65, v64, vcc
	v_not_b32_e32 v64, v58
	v_or_b32_e32 v65, 0x80000000, v58
	v_cmp_gt_i32_e32 vcc, 0, v58
	v_and_b32_e32 v9, 0xffffff80, v9
	v_bitop3_b32 v9, v9, 31, v174 bitop3:0x36
	v_cndmask_b32_e32 v58, v65, v64, vcc
	v_not_b32_e32 v64, v42
	v_or_b32_e32 v65, 0x80000000, v42
	v_cmp_gt_i32_e32 vcc, 0, v42
	v_and_b32_e32 v58, 0xffffff80, v58
	v_bitop3_b32 v58, v58, s39, v175 bitop3:0x36
	v_cndmask_b32_e32 v42, v65, v64, vcc
	v_not_b32_e32 v64, v26
	v_or_b32_e32 v65, 0x80000000, v26
	v_cmp_gt_i32_e32 vcc, 0, v26
	v_and_b32_e32 v42, 0xffffff80, v42
	v_bitop3_b32 v42, v42, s38, v175 bitop3:0x36
	v_cndmask_b32_e32 v26, v65, v64, vcc
	v_not_b32_e32 v64, v10
	v_or_b32_e32 v65, 0x80000000, v10
	v_cmp_gt_i32_e32 vcc, 0, v10
	v_and_b32_e32 v26, 0xffffff80, v26
	v_bitop3_b32 v26, v26, 63, v175 bitop3:0x36
	v_cndmask_b32_e32 v10, v65, v64, vcc
	v_not_b32_e32 v64, v59
	v_or_b32_e32 v65, 0x80000000, v59
	v_cmp_gt_i32_e32 vcc, 0, v59
	v_and_b32_e32 v10, 0xffffff80, v10
	v_bitop3_b32 v10, v10, 31, v175 bitop3:0x36
	v_cndmask_b32_e32 v59, v65, v64, vcc
	v_not_b32_e32 v64, v43
	v_or_b32_e32 v65, 0x80000000, v43
	v_cmp_gt_i32_e32 vcc, 0, v43
	v_and_b32_e32 v59, 0xffffff80, v59
	v_bitop3_b32 v59, v59, s39, v179 bitop3:0x36
	v_cndmask_b32_e32 v43, v65, v64, vcc
	v_not_b32_e32 v64, v27
	v_or_b32_e32 v65, 0x80000000, v27
	v_cmp_gt_i32_e32 vcc, 0, v27
	v_and_b32_e32 v43, 0xffffff80, v43
	v_bitop3_b32 v43, v43, s38, v179 bitop3:0x36
	v_cndmask_b32_e32 v27, v65, v64, vcc
	v_not_b32_e32 v64, v11
	v_or_b32_e32 v65, 0x80000000, v11
	v_cmp_gt_i32_e32 vcc, 0, v11
	v_and_b32_e32 v27, 0xffffff80, v27
	v_bitop3_b32 v27, v27, 63, v179 bitop3:0x36
	v_cndmask_b32_e32 v11, v65, v64, vcc
	v_not_b32_e32 v64, v60
	v_or_b32_e32 v65, 0x80000000, v60
	v_cmp_gt_i32_e32 vcc, 0, v60
	v_and_b32_e32 v11, 0xffffff80, v11
	v_bitop3_b32 v11, v11, 31, v179 bitop3:0x36
	v_cndmask_b32_e32 v60, v65, v64, vcc
	v_not_b32_e32 v64, v44
	v_or_b32_e32 v65, 0x80000000, v44
	v_cmp_gt_i32_e32 vcc, 0, v44
	v_and_b32_e32 v60, 0xffffff80, v60
	v_bitop3_b32 v60, v60, s39, v170 bitop3:0x36
	v_cndmask_b32_e32 v44, v65, v64, vcc
	v_not_b32_e32 v64, v28
	v_or_b32_e32 v65, 0x80000000, v28
	v_cmp_gt_i32_e32 vcc, 0, v28
	v_and_b32_e32 v44, 0xffffff80, v44
	v_bitop3_b32 v44, v44, s38, v170 bitop3:0x36
	v_cndmask_b32_e32 v28, v65, v64, vcc
	v_not_b32_e32 v64, v12
	v_or_b32_e32 v65, 0x80000000, v12
	v_cmp_gt_i32_e32 vcc, 0, v12
	v_and_b32_e32 v28, 0xffffff80, v28
	v_bitop3_b32 v28, v28, 63, v170 bitop3:0x36
	v_cndmask_b32_e32 v12, v65, v64, vcc
	v_not_b32_e32 v64, v61
	v_or_b32_e32 v65, 0x80000000, v61
	v_cmp_gt_i32_e32 vcc, 0, v61
	v_and_b32_e32 v12, 0xffffff80, v12
	v_bitop3_b32 v12, v12, 31, v170 bitop3:0x36
	v_cndmask_b32_e32 v61, v65, v64, vcc
	v_not_b32_e32 v64, v45
	v_or_b32_e32 v65, 0x80000000, v45
	v_cmp_gt_i32_e32 vcc, 0, v45
	v_and_b32_e32 v61, 0xffffff80, v61
	v_bitop3_b32 v61, v61, s39, v180 bitop3:0x36
	v_cndmask_b32_e32 v45, v65, v64, vcc
	v_not_b32_e32 v64, v29
	v_or_b32_e32 v65, 0x80000000, v29
	v_cmp_gt_i32_e32 vcc, 0, v29
	v_and_b32_e32 v45, 0xffffff80, v45
	v_bitop3_b32 v45, v45, s38, v180 bitop3:0x36
; DEV unsigned fkey(float v) { const unsigned u = __float_as_uint(v); return (u & 0x80000000u) ? ~u : (u | 0x80000000u); }
; DEV void sort16_desc(unsigned (&x)[16]) {
; #pragma unroll
;   for (int k = 2; k <= 16; k <<= 1)
; #pragma unroll
;     for (int j = k >> 1; j > 0; j >>= 1)
; #pragma unroll
;       for (int i = 0; i < 16; ++i) {
;         const int p = i ^ j;
;         if (p > i) {
;           if ((i & k) == 0) { TK_CE(x[i], x[p]); } else { TK_CE(x[p], x[i]); }
;         }
;       }
; }
; __device__ void peer_q_topk_item(const Params& P, int l, int item, char* smem) {
;     ...
;       unsigned G1[16], G2[16], G3[16];
; #pragma unroll
;       for (int i = 0; i < 16; ++i) {
;         const int kb0 = (i & 3) + 8 * (i >> 2) + 4 * hk;
;         Lc[i] = (fkey(sa[0][i]) & ~0x7Fu) | (unsigned)(127 - kb0);
;         G1[i] = (fkey(sa[1][i]) & ~0x7Fu) | (unsigned)(127 - (32 + kb0));
;         G2[i] = (fkey(sa[2][i]) & ~0x7Fu) | (unsigned)(127 - (64 + kb0));
;         G3[i] = (fkey(sa[3][i]) & ~0x7Fu) | (unsigned)(127 - (96 + kb0));
;       }
;       sort16_desc(Lc); sort16_desc(G1); sort16_desc(G2); sort16_desc(G3);
	v_cndmask_b32_e32 v29, v65, v64, vcc
	v_not_b32_e32 v64, v13
	v_or_b32_e32 v65, 0x80000000, v13
	v_cmp_gt_i32_e32 vcc, 0, v13
	v_and_b32_e32 v29, 0xffffff80, v29
	v_bitop3_b32 v29, v29, 63, v180 bitop3:0x36
	v_cndmask_b32_e32 v13, v65, v64, vcc
	v_not_b32_e32 v64, v62
	v_or_b32_e32 v65, 0x80000000, v62
	v_cmp_gt_i32_e32 vcc, 0, v62
	v_and_b32_e32 v13, 0xffffff80, v13
	v_bitop3_b32 v13, v13, 31, v180 bitop3:0x36
	v_cndmask_b32_e32 v62, v65, v64, vcc
	v_not_b32_e32 v64, v46
	v_or_b32_e32 v65, 0x80000000, v46
	v_cmp_gt_i32_e32 vcc, 0, v46
	v_and_b32_e32 v62, 0xffffff80, v62
	v_bitop3_b32 v62, v62, s39, v181 bitop3:0x36
	v_cndmask_b32_e32 v46, v65, v64, vcc
	v_not_b32_e32 v64, v30
	v_or_b32_e32 v65, 0x80000000, v30
	v_cmp_gt_i32_e32 vcc, 0, v30
	v_and_b32_e32 v46, 0xffffff80, v46
	v_bitop3_b32 v46, v46, s38, v181 bitop3:0x36
	v_cndmask_b32_e32 v30, v65, v64, vcc
	v_not_b32_e32 v64, v14
	v_or_b32_e32 v65, 0x80000000, v14
	v_cmp_gt_i32_e32 vcc, 0, v14
	v_and_b32_e32 v30, 0xffffff80, v30
	v_bitop3_b32 v30, v30, 63, v181 bitop3:0x36
	v_cndmask_b32_e32 v14, v65, v64, vcc
	v_not_b32_e32 v64, v63
	v_or_b32_e32 v65, 0x80000000, v63
	v_cmp_gt_i32_e32 vcc, 0, v63
	v_and_b32_e32 v14, 0xffffff80, v14
	v_bitop3_b32 v14, v14, 31, v181 bitop3:0x36
	v_cndmask_b32_e32 v63, v65, v64, vcc
	v_not_b32_e32 v64, v47
	v_or_b32_e32 v65, 0x80000000, v47
	v_cmp_gt_i32_e32 vcc, 0, v47
	v_and_b32_e32 v63, 0xffffff80, v63
	v_bitop3_b32 v63, v63, s39, v182 bitop3:0x36
	v_cndmask_b32_e32 v47, v65, v64, vcc
	v_not_b32_e32 v64, v31
	v_or_b32_e32 v65, 0x80000000, v31
	v_cmp_gt_i32_e32 vcc, 0, v31
	v_and_b32_e32 v47, 0xffffff80, v47
	v_bitop3_b32 v47, v47, s38, v182 bitop3:0x36
	v_cndmask_b32_e32 v31, v65, v64, vcc
	v_not_b32_e32 v64, v15
	v_or_b32_e32 v65, 0x80000000, v15
	v_cmp_gt_i32_e32 vcc, 0, v15
	v_and_b32_e32 v31, 0xffffff80, v31
	v_bitop3_b32 v31, v31, 63, v182 bitop3:0x36
	v_cndmask_b32_e32 v15, v65, v64, vcc
	v_and_b32_e32 v15, 0xffffff80, v15
	v_bitop3_b32 v15, v15, 31, v182 bitop3:0x36
	v_max_u32_e32 v64, v48, v49
	v_min_u32_e32 v48, v48, v49
	v_max_u32_e32 v49, v51, v50
	v_min_u32_e32 v50, v51, v50
	v_max_u32_e32 v51, v52, v53
	v_min_u32_e32 v52, v52, v53
	v_max_u32_e32 v53, v55, v54
	v_min_u32_e32 v54, v55, v54
	v_max_u32_e32 v55, v56, v57
	v_min_u32_e32 v56, v56, v57
	v_max_u32_e32 v57, v59, v58
	v_min_u32_e32 v58, v59, v58
	v_max_u32_e32 v59, v60, v61
	v_min_u32_e32 v60, v60, v61
	v_max_u32_e32 v61, v63, v62
	v_min_u32_e32 v62, v63, v62
	v_max_u32_e32 v72, v32, v33
	v_min_u32_e32 v32, v32, v33
	v_max_u32_e32 v33, v35, v34
	v_min_u32_e32 v34, v35, v34
	v_max_u32_e32 v35, v36, v37
	v_min_u32_e32 v36, v36, v37
	v_max_u32_e32 v37, v39, v38
	v_min_u32_e32 v38, v39, v38
	v_max_u32_e32 v39, v40, v41
	v_min_u32_e32 v40, v40, v41
	v_max_u32_e32 v41, v43, v42
	v_min_u32_e32 v42, v43, v42
	v_max_u32_e32 v43, v44, v45
	v_min_u32_e32 v44, v44, v45
	v_max_u32_e32 v45, v47, v46
	v_min_u32_e32 v46, v47, v46
	v_max_u32_e32 v80, v16, v17
	v_min_u32_e32 v16, v16, v17
	v_max_u32_e32 v17, v19, v18
	v_min_u32_e32 v18, v19, v18
	v_max_u32_e32 v19, v20, v21
	v_min_u32_e32 v20, v20, v21
	v_max_u32_e32 v21, v23, v22
	v_min_u32_e32 v22, v23, v22
	v_max_u32_e32 v23, v24, v25
	v_min_u32_e32 v24, v24, v25
	v_max_u32_e32 v25, v27, v26
	v_min_u32_e32 v26, v27, v26
	v_max_u32_e32 v27, v28, v29
	v_min_u32_e32 v28, v28, v29
	v_max_u32_e32 v29, v31, v30
	v_min_u32_e32 v30, v31, v30
	v_max_u32_e32 v88, v0, v1
	v_min_u32_e32 v0, v0, v1
	v_max_u32_e32 v1, v3, v2
	v_min_u32_e32 v2, v3, v2
	v_max_u32_e32 v3, v4, v5
	v_min_u32_e32 v4, v4, v5
	v_max_u32_e32 v5, v7, v6
	v_min_u32_e32 v6, v7, v6
	v_max_u32_e32 v7, v8, v9
	v_min_u32_e32 v8, v8, v9
	v_max_u32_e32 v9, v11, v10
	v_min_u32_e32 v10, v11, v10
	v_max_u32_e32 v11, v12, v13
	v_min_u32_e32 v12, v12, v13
	v_max_u32_e32 v13, v15, v14
	v_min_u32_e32 v14, v15, v14
	v_max_u32_e32 v63, v64, v50
	v_min_u32_e32 v50, v64, v50
	v_max_u32_e32 v64, v48, v49
	v_min_u32_e32 v48, v48, v49
	v_max_u32_e32 v49, v54, v51
	v_min_u32_e32 v51, v54, v51
	v_max_u32_e32 v54, v53, v52
	v_min_u32_e32 v52, v53, v52
	v_max_u32_e32 v53, v55, v58
	v_min_u32_e32 v55, v55, v58
	v_max_u32_e32 v58, v56, v57
	v_min_u32_e32 v56, v56, v57
	v_max_u32_e32 v57, v62, v59
	v_min_u32_e32 v59, v62, v59
	v_max_u32_e32 v62, v61, v60
	v_min_u32_e32 v60, v61, v60
	v_max_u32_e32 v47, v72, v34
	v_min_u32_e32 v34, v72, v34
	v_max_u32_e32 v72, v32, v33
	v_min_u32_e32 v32, v32, v33
	v_max_u32_e32 v33, v38, v35
	v_min_u32_e32 v35, v38, v35
	v_max_u32_e32 v38, v37, v36
	v_min_u32_e32 v36, v37, v36
	v_max_u32_e32 v37, v39, v42
	v_min_u32_e32 v39, v39, v42
	v_max_u32_e32 v42, v40, v41
	v_min_u32_e32 v40, v40, v41
	v_max_u32_e32 v41, v46, v43
	v_min_u32_e32 v43, v46, v43
	v_max_u32_e32 v46, v45, v44
	v_min_u32_e32 v44, v45, v44
	v_max_u32_e32 v31, v80, v18
	v_min_u32_e32 v18, v80, v18
	v_max_u32_e32 v80, v16, v17
	v_min_u32_e32 v16, v16, v17
	v_max_u32_e32 v17, v22, v19
	v_min_u32_e32 v19, v22, v19
	v_max_u32_e32 v22, v21, v20
	v_min_u32_e32 v20, v21, v20
	v_max_u32_e32 v21, v23, v26
	v_min_u32_e32 v23, v23, v26
	v_max_u32_e32 v26, v24, v25
	v_min_u32_e32 v24, v24, v25
	v_max_u32_e32 v25, v30, v27
	v_min_u32_e32 v27, v30, v27
	v_max_u32_e32 v30, v29, v28
	v_min_u32_e32 v28, v29, v28
	v_max_u32_e32 v15, v88, v2
	v_min_u32_e32 v2, v88, v2
	v_max_u32_e32 v88, v0, v1
	v_min_u32_e32 v0, v0, v1
	v_max_u32_e32 v1, v6, v3
	v_min_u32_e32 v3, v6, v3
	v_max_u32_e32 v6, v5, v4
	v_min_u32_e32 v4, v5, v4
	v_max_u32_e32 v5, v7, v10
	v_min_u32_e32 v7, v7, v10
	v_max_u32_e32 v10, v8, v9
	v_min_u32_e32 v8, v8, v9
	v_max_u32_e32 v9, v14, v11
	v_min_u32_e32 v11, v14, v11
	v_max_u32_e32 v14, v13, v12
	v_min_u32_e32 v12, v13, v12
; DEV void sort16_desc(unsigned (&x)[16]) {
; #pragma unroll
;   for (int k = 2; k <= 16; k <<= 1)
; #pragma unroll
;     for (int j = k >> 1; j > 0; j >>= 1)
; #pragma unroll
;       for (int i = 0; i < 16; ++i) {
;         const int p = i ^ j;
;         if (p > i) {
;           if ((i & k) == 0) { TK_CE(x[i], x[p]); } else { TK_CE(x[p], x[i]); }
;         }
;       }
; }
	v_max_u32_e32 v61, v63, v64
	v_min_u32_e32 v63, v63, v64
	v_max_u32_e32 v64, v50, v48
	v_min_u32_e32 v48, v50, v48
	v_max_u32_e32 v50, v52, v51
	v_min_u32_e32 v51, v52, v51
	v_max_u32_e32 v52, v54, v49
	v_min_u32_e32 v49, v54, v49
	v_max_u32_e32 v54, v53, v58
	v_min_u32_e32 v53, v53, v58
	v_max_u32_e32 v58, v55, v56
	v_min_u32_e32 v55, v55, v56
	v_max_u32_e32 v56, v60, v59
	v_min_u32_e32 v59, v60, v59
	v_max_u32_e32 v60, v62, v57
	v_min_u32_e32 v57, v62, v57
	v_max_u32_e32 v45, v47, v72
	v_min_u32_e32 v47, v47, v72
	v_max_u32_e32 v72, v34, v32
	v_min_u32_e32 v32, v34, v32
	v_max_u32_e32 v34, v36, v35
	v_min_u32_e32 v35, v36, v35
	v_max_u32_e32 v36, v38, v33
	v_min_u32_e32 v33, v38, v33
	v_max_u32_e32 v38, v37, v42
	v_min_u32_e32 v37, v37, v42
	v_max_u32_e32 v42, v39, v40
	v_min_u32_e32 v39, v39, v40
	v_max_u32_e32 v40, v44, v43
	v_min_u32_e32 v43, v44, v43
	v_max_u32_e32 v44, v46, v41
	v_min_u32_e32 v41, v46, v41
	v_max_u32_e32 v29, v31, v80
	v_min_u32_e32 v31, v31, v80
	v_max_u32_e32 v80, v18, v16
	v_min_u32_e32 v16, v18, v16
	v_max_u32_e32 v18, v20, v19
	v_min_u32_e32 v19, v20, v19
	v_max_u32_e32 v20, v22, v17
	v_min_u32_e32 v17, v22, v17
	v_max_u32_e32 v22, v21, v26
	v_min_u32_e32 v21, v21, v26
	v_max_u32_e32 v26, v23, v24
	v_min_u32_e32 v23, v23, v24
	v_max_u32_e32 v24, v28, v27
	v_min_u32_e32 v27, v28, v27
	v_max_u32_e32 v28, v30, v25
	v_min_u32_e32 v25, v30, v25
	v_max_u32_e32 v13, v15, v88
	v_min_u32_e32 v15, v15, v88
	v_max_u32_e32 v88, v2, v0
	v_min_u32_e32 v0, v2, v0
	v_max_u32_e32 v2, v4, v3
	v_min_u32_e32 v3, v4, v3
	v_max_u32_e32 v4, v6, v1
	v_min_u32_e32 v1, v6, v1
	v_max_u32_e32 v6, v5, v10
	v_min_u32_e32 v5, v5, v10
	v_max_u32_e32 v10, v7, v8
	v_min_u32_e32 v7, v7, v8
	v_max_u32_e32 v8, v12, v11
	v_min_u32_e32 v11, v12, v11
	v_max_u32_e32 v12, v14, v9
	v_min_u32_e32 v9, v14, v9
	v_max_u32_e32 v62, v61, v51
	v_min_u32_e32 v51, v61, v51
	v_max_u32_e32 v61, v63, v50
	v_min_u32_e32 v50, v63, v50
	v_max_u32_e32 v63, v64, v49
	v_min_u32_e32 v49, v64, v49
	v_max_u32_e32 v64, v48, v52
	v_min_u32_e32 v48, v48, v52
	v_max_u32_e32 v52, v59, v54
	v_min_u32_e32 v54, v59, v54
	v_max_u32_e32 v59, v56, v53
	v_min_u32_e32 v53, v56, v53
	v_max_u32_e32 v56, v57, v58
	v_min_u32_e32 v57, v57, v58
	v_max_u32_e32 v58, v60, v55
	v_min_u32_e32 v55, v60, v55
	v_max_u32_e32 v46, v45, v35
	v_min_u32_e32 v35, v45, v35
	v_max_u32_e32 v45, v47, v34
	v_min_u32_e32 v34, v47, v34
	v_max_u32_e32 v47, v72, v33
	v_min_u32_e32 v33, v72, v33
	v_max_u32_e32 v72, v32, v36
	v_min_u32_e32 v32, v32, v36
	v_max_u32_e32 v36, v43, v38
	v_min_u32_e32 v38, v43, v38
	v_max_u32_e32 v43, v40, v37
	v_min_u32_e32 v37, v40, v37
	v_max_u32_e32 v40, v41, v42
	v_min_u32_e32 v41, v41, v42
	v_max_u32_e32 v42, v44, v39
	v_min_u32_e32 v39, v44, v39
	v_max_u32_e32 v30, v29, v19
	v_min_u32_e32 v19, v29, v19
	v_max_u32_e32 v29, v31, v18
	v_min_u32_e32 v18, v31, v18
	v_max_u32_e32 v31, v80, v17
	v_min_u32_e32 v17, v80, v17
	v_max_u32_e32 v80, v16, v20
	v_min_u32_e32 v16, v16, v20
	v_max_u32_e32 v20, v27, v22
	v_min_u32_e32 v22, v27, v22
	v_max_u32_e32 v27, v24, v21
	v_min_u32_e32 v21, v24, v21
	v_max_u32_e32 v24, v25, v26
	v_min_u32_e32 v25, v25, v26
	v_max_u32_e32 v26, v28, v23
	v_min_u32_e32 v23, v28, v23
	v_max_u32_e32 v14, v13, v3
	v_min_u32_e32 v3, v13, v3
	v_max_u32_e32 v13, v15, v2
	v_min_u32_e32 v2, v15, v2
	v_max_u32_e32 v15, v88, v1
	v_min_u32_e32 v1, v88, v1
	v_max_u32_e32 v88, v0, v4
	v_min_u32_e32 v0, v0, v4
	v_max_u32_e32 v4, v11, v6
	v_min_u32_e32 v6, v11, v6
	v_max_u32_e32 v11, v8, v5
	v_min_u32_e32 v5, v8, v5
	v_max_u32_e32 v8, v9, v10
	v_min_u32_e32 v9, v9, v10
	v_max_u32_e32 v10, v12, v7
	v_min_u32_e32 v7, v12, v7
	v_max_u32_e32 v60, v62, v63
	v_min_u32_e32 v62, v62, v63
	v_max_u32_e32 v63, v61, v64
	v_min_u32_e32 v61, v61, v64
	v_max_u32_e32 v64, v51, v49
	v_min_u32_e32 v49, v51, v49
	v_max_u32_e32 v51, v50, v48
	v_min_u32_e32 v48, v50, v48
	v_max_u32_e32 v50, v57, v54
	v_min_u32_e32 v54, v57, v54
	v_max_u32_e32 v57, v55, v53
	v_min_u32_e32 v53, v55, v53
	v_max_u32_e32 v55, v56, v52
	v_min_u32_e32 v52, v56, v52
	v_max_u32_e32 v56, v58, v59
	v_min_u32_e32 v58, v58, v59
	v_max_u32_e32 v44, v46, v47
	v_min_u32_e32 v46, v46, v47
	v_max_u32_e32 v47, v45, v72
	v_min_u32_e32 v45, v45, v72
	v_max_u32_e32 v72, v35, v33
	v_min_u32_e32 v33, v35, v33
	v_max_u32_e32 v35, v34, v32
	v_min_u32_e32 v32, v34, v32
	v_max_u32_e32 v34, v41, v38
	v_min_u32_e32 v38, v41, v38
	v_max_u32_e32 v41, v39, v37
	v_min_u32_e32 v37, v39, v37
	v_max_u32_e32 v39, v40, v36
	v_min_u32_e32 v36, v40, v36
	v_max_u32_e32 v40, v42, v43
	v_min_u32_e32 v42, v42, v43
	v_max_u32_e32 v28, v30, v31
	v_min_u32_e32 v30, v30, v31
	v_max_u32_e32 v31, v29, v80
	v_min_u32_e32 v29, v29, v80
	v_max_u32_e32 v80, v19, v17
	v_min_u32_e32 v17, v19, v17
	v_max_u32_e32 v19, v18, v16
	v_min_u32_e32 v16, v18, v16
	v_max_u32_e32 v18, v25, v22
	v_min_u32_e32 v22, v25, v22
	v_max_u32_e32 v25, v23, v21
	v_min_u32_e32 v21, v23, v21
	v_max_u32_e32 v23, v24, v20
	v_min_u32_e32 v20, v24, v20
	v_max_u32_e32 v24, v26, v27
	v_min_u32_e32 v26, v26, v27
	v_max_u32_e32 v12, v14, v15
	v_min_u32_e32 v14, v14, v15
	v_max_u32_e32 v15, v13, v88
	v_min_u32_e32 v13, v13, v88
	v_max_u32_e32 v88, v3, v1
	v_min_u32_e32 v1, v3, v1
	v_max_u32_e32 v3, v2, v0
	v_min_u32_e32 v0, v2, v0
	v_max_u32_e32 v2, v9, v6
	v_min_u32_e32 v6, v9, v6
	v_max_u32_e32 v9, v7, v5
	v_min_u32_e32 v5, v7, v5
	v_max_u32_e32 v7, v8, v4
	v_min_u32_e32 v4, v8, v4
	v_max_u32_e32 v8, v10, v11
	v_min_u32_e32 v10, v10, v11
	v_max_u32_e32 v59, v60, v63
	v_min_u32_e32 v60, v60, v63
	v_max_u32_e32 v63, v62, v61
	v_min_u32_e32 v61, v62, v61
	v_max_u32_e32 v62, v64, v51
	v_min_u32_e32 v51, v64, v51
; DEV void sort16_desc(unsigned (&x)[16]) {
; #pragma unroll
;   for (int k = 2; k <= 16; k <<= 1)
; #pragma unroll
;     for (int j = k >> 1; j > 0; j >>= 1)
; #pragma unroll
;       for (int i = 0; i < 16; ++i) {
;         const int p = i ^ j;
;         if (p > i) {
;           if ((i & k) == 0) { TK_CE(x[i], x[p]); } else { TK_CE(x[p], x[i]); }
;         }
;       }
; }
	v_max_u32_e32 v64, v49, v48
	v_min_u32_e32 v48, v49, v48
	v_max_u32_e32 v49, v53, v54
	v_min_u32_e32 v53, v53, v54
	v_max_u32_e32 v54, v57, v50
	v_min_u32_e32 v50, v57, v50
	v_max_u32_e32 v57, v58, v52
	v_min_u32_e32 v52, v58, v52
	v_max_u32_e32 v58, v56, v55
	v_min_u32_e32 v55, v56, v55
	v_max_u32_e32 v43, v44, v47
	v_min_u32_e32 v44, v44, v47
	v_max_u32_e32 v47, v46, v45
	v_min_u32_e32 v45, v46, v45
	v_max_u32_e32 v46, v72, v35
	v_min_u32_e32 v35, v72, v35
	v_max_u32_e32 v72, v33, v32
	v_min_u32_e32 v32, v33, v32
	v_max_u32_e32 v33, v37, v38
	v_min_u32_e32 v37, v37, v38
	v_max_u32_e32 v38, v41, v34
	v_min_u32_e32 v34, v41, v34
	v_max_u32_e32 v41, v42, v36
	v_min_u32_e32 v36, v42, v36
	v_max_u32_e32 v42, v40, v39
	v_min_u32_e32 v39, v40, v39
	v_max_u32_e32 v27, v28, v31
	v_min_u32_e32 v28, v28, v31
	v_max_u32_e32 v31, v30, v29
	v_min_u32_e32 v29, v30, v29
	v_max_u32_e32 v30, v80, v19
	v_min_u32_e32 v19, v80, v19
	v_max_u32_e32 v80, v17, v16
	v_min_u32_e32 v16, v17, v16
	v_max_u32_e32 v17, v21, v22
	v_min_u32_e32 v21, v21, v22
	v_max_u32_e32 v22, v25, v18
	v_min_u32_e32 v18, v25, v18
	v_max_u32_e32 v25, v26, v20
	v_min_u32_e32 v20, v26, v20
	v_max_u32_e32 v26, v24, v23
	v_min_u32_e32 v23, v24, v23
	v_max_u32_e32 v11, v12, v15
	v_min_u32_e32 v12, v12, v15
	v_max_u32_e32 v15, v14, v13
	v_min_u32_e32 v13, v14, v13
	v_max_u32_e32 v14, v88, v3
	v_min_u32_e32 v3, v88, v3
	v_max_u32_e32 v88, v1, v0
	v_min_u32_e32 v0, v1, v0
	v_max_u32_e32 v1, v5, v6
	v_min_u32_e32 v5, v5, v6
	v_max_u32_e32 v6, v9, v2
	v_min_u32_e32 v2, v9, v2
	v_max_u32_e32 v9, v10, v4
	v_min_u32_e32 v4, v10, v4
	v_max_u32_e32 v10, v8, v7
	v_min_u32_e32 v7, v8, v7
	v_max_u32_e32 v56, v59, v53
	v_min_u32_e32 v53, v59, v53
	v_max_u32_e32 v59, v60, v49
	v_min_u32_e32 v49, v60, v49
	v_max_u32_e32 v60, v63, v50
	v_min_u32_e32 v50, v63, v50
	v_max_u32_e32 v63, v61, v54
	v_min_u32_e32 v54, v61, v54
	v_max_u32_e32 v61, v62, v52
	v_min_u32_e32 v52, v62, v52
	v_max_u32_e32 v62, v51, v57
	v_min_u32_e32 v51, v51, v57
	v_max_u32_e32 v57, v64, v55
	v_min_u32_e32 v55, v64, v55
	v_max_u32_e32 v64, v48, v58
	v_min_u32_e32 v48, v48, v58
	v_max_u32_e32 v40, v43, v37
	v_min_u32_e32 v37, v43, v37
	v_max_u32_e32 v43, v44, v33
	v_min_u32_e32 v33, v44, v33
	v_max_u32_e32 v44, v47, v34
	v_min_u32_e32 v34, v47, v34
	v_max_u32_e32 v47, v45, v38
	v_min_u32_e32 v38, v45, v38
	v_max_u32_e32 v45, v46, v36
	v_min_u32_e32 v36, v46, v36
	v_max_u32_e32 v46, v35, v41
	v_min_u32_e32 v35, v35, v41
	v_max_u32_e32 v41, v72, v39
	v_min_u32_e32 v39, v72, v39
	v_max_u32_e32 v72, v32, v42
	v_min_u32_e32 v32, v32, v42
	v_max_u32_e32 v24, v27, v21
	v_min_u32_e32 v21, v27, v21
	v_max_u32_e32 v27, v28, v17
	v_min_u32_e32 v17, v28, v17
	v_max_u32_e32 v28, v31, v18
	v_min_u32_e32 v18, v31, v18
	v_max_u32_e32 v31, v29, v22
	v_min_u32_e32 v22, v29, v22
	v_max_u32_e32 v29, v30, v20
	v_min_u32_e32 v20, v30, v20
	v_max_u32_e32 v30, v19, v25
	v_min_u32_e32 v19, v19, v25
	v_max_u32_e32 v25, v80, v23
	v_min_u32_e32 v23, v80, v23
	v_max_u32_e32 v80, v16, v26
	v_min_u32_e32 v16, v16, v26
	v_max_u32_e32 v8, v11, v5
	v_min_u32_e32 v5, v11, v5
	v_max_u32_e32 v11, v12, v1
	v_min_u32_e32 v1, v12, v1
	v_max_u32_e32 v12, v15, v2
	v_min_u32_e32 v2, v15, v2
	v_max_u32_e32 v15, v13, v6
	v_min_u32_e32 v6, v13, v6
	v_max_u32_e32 v13, v14, v4
	v_min_u32_e32 v4, v14, v4
	v_max_u32_e32 v14, v3, v9
	v_min_u32_e32 v3, v3, v9
	v_max_u32_e32 v9, v88, v7
	v_min_u32_e32 v7, v88, v7
	v_max_u32_e32 v88, v0, v10
	v_min_u32_e32 v0, v0, v10
	v_max_u32_e32 v58, v56, v61
	v_min_u32_e32 v56, v56, v61
	v_max_u32_e32 v61, v59, v62
	v_min_u32_e32 v59, v59, v62
	v_max_u32_e32 v62, v60, v57
	v_min_u32_e32 v57, v60, v57
	v_max_u32_e32 v60, v63, v64
	v_min_u32_e32 v63, v63, v64
	v_max_u32_e32 v64, v53, v52
	v_min_u32_e32 v52, v53, v52
	v_max_u32_e32 v53, v49, v51
	v_min_u32_e32 v49, v49, v51
	v_max_u32_e32 v51, v50, v55
	v_min_u32_e32 v50, v50, v55
	v_max_u32_e32 v55, v54, v48
	v_min_u32_e32 v48, v54, v48
	v_max_u32_e32 v42, v40, v45
	v_min_u32_e32 v40, v40, v45
	v_max_u32_e32 v45, v43, v46
	v_min_u32_e32 v43, v43, v46
	v_max_u32_e32 v46, v44, v41
	v_min_u32_e32 v41, v44, v41
	v_max_u32_e32 v44, v47, v72
	v_min_u32_e32 v47, v47, v72
	v_max_u32_e32 v72, v37, v36
	v_min_u32_e32 v36, v37, v36
	v_max_u32_e32 v37, v33, v35
	v_min_u32_e32 v33, v33, v35
	v_max_u32_e32 v35, v34, v39
	v_min_u32_e32 v34, v34, v39
	v_max_u32_e32 v39, v38, v32
	v_min_u32_e32 v32, v38, v32
	v_max_u32_e32 v26, v24, v29
	v_min_u32_e32 v24, v24, v29
	v_max_u32_e32 v29, v27, v30
	v_min_u32_e32 v27, v27, v30
	v_max_u32_e32 v30, v28, v25
	v_min_u32_e32 v25, v28, v25
	v_max_u32_e32 v28, v31, v80
	v_min_u32_e32 v31, v31, v80
	v_max_u32_e32 v80, v21, v20
	v_min_u32_e32 v20, v21, v20
	v_max_u32_e32 v21, v17, v19
	v_min_u32_e32 v17, v17, v19
	v_max_u32_e32 v19, v18, v23
	v_min_u32_e32 v18, v18, v23
	v_max_u32_e32 v23, v22, v16
	v_min_u32_e32 v16, v22, v16
	v_max_u32_e32 v10, v8, v13
	v_min_u32_e32 v8, v8, v13
	v_max_u32_e32 v13, v11, v14
	v_min_u32_e32 v11, v11, v14
	v_max_u32_e32 v14, v12, v9
	v_min_u32_e32 v9, v12, v9
	v_max_u32_e32 v12, v15, v88
	v_min_u32_e32 v15, v15, v88
	v_max_u32_e32 v88, v5, v4
	v_min_u32_e32 v4, v5, v4
	v_max_u32_e32 v5, v1, v3
	v_min_u32_e32 v1, v1, v3
	v_max_u32_e32 v3, v2, v7
	v_min_u32_e32 v2, v2, v7
	v_max_u32_e32 v7, v6, v0
	v_min_u32_e32 v0, v6, v0
	v_max_u32_e32 v54, v58, v62
	v_min_u32_e32 v58, v58, v62
	v_max_u32_e32 v62, v61, v60
	v_min_u32_e32 v60, v61, v60
	v_max_u32_e32 v61, v56, v57
	v_min_u32_e32 v56, v56, v57
	v_max_u32_e32 v57, v59, v63
	v_min_u32_e32 v59, v59, v63
	v_max_u32_e32 v63, v64, v51
	v_min_u32_e32 v51, v64, v51
	v_max_u32_e32 v64, v53, v55
; DEV void sort16_desc(unsigned (&x)[16]) {
; #pragma unroll
;   for (int k = 2; k <= 16; k <<= 1)
; #pragma unroll
;     for (int j = k >> 1; j > 0; j >>= 1)
; #pragma unroll
;       for (int i = 0; i < 16; ++i) {
;         const int p = i ^ j;
;         if (p > i) {
;           if ((i & k) == 0) { TK_CE(x[i], x[p]); } else { TK_CE(x[p], x[i]); }
;         }
;       }
; }
; DEV void merge_top16(unsigned (&x)[16], const unsigned (&y)[16]) {
; #pragma unroll
;   for (int i = 0; i < 16; ++i) x[i] = max(x[i], y[15 - i]);
; #pragma unroll
;   for (int j = 8; j > 0; j >>= 1)
; #pragma unroll
;     for (int i = 0; i < 16; ++i) {
;       const int p = i ^ j;
;       if (p > i) { TK_CE(x[i], x[p]); }
;     }
; }
	v_min_u32_e32 v53, v53, v55
	v_max_u32_e32 v55, v52, v50
	v_min_u32_e32 v50, v52, v50
	v_max_u32_e32 v52, v49, v48
	v_min_u32_e32 v48, v49, v48
	v_max_u32_e32 v38, v42, v46
	v_min_u32_e32 v42, v42, v46
	v_max_u32_e32 v46, v45, v44
	v_min_u32_e32 v44, v45, v44
	v_max_u32_e32 v45, v40, v41
	v_min_u32_e32 v40, v40, v41
	v_max_u32_e32 v41, v43, v47
	v_min_u32_e32 v43, v43, v47
	v_max_u32_e32 v47, v72, v35
	v_min_u32_e32 v35, v72, v35
	v_max_u32_e32 v72, v37, v39
	v_min_u32_e32 v37, v37, v39
	v_max_u32_e32 v39, v36, v34
	v_min_u32_e32 v34, v36, v34
	v_max_u32_e32 v36, v33, v32
	v_min_u32_e32 v32, v33, v32
	v_max_u32_e32 v22, v26, v30
	v_min_u32_e32 v26, v26, v30
	v_max_u32_e32 v30, v29, v28
	v_min_u32_e32 v28, v29, v28
	v_max_u32_e32 v29, v24, v25
	v_min_u32_e32 v24, v24, v25
	v_max_u32_e32 v25, v27, v31
	v_min_u32_e32 v27, v27, v31
	v_max_u32_e32 v31, v80, v19
	v_min_u32_e32 v19, v80, v19
	v_max_u32_e32 v80, v21, v23
	v_min_u32_e32 v21, v21, v23
	v_max_u32_e32 v23, v20, v18
	v_min_u32_e32 v18, v20, v18
	v_max_u32_e32 v20, v17, v16
	v_min_u32_e32 v16, v17, v16
	v_max_u32_e32 v6, v10, v14
	v_min_u32_e32 v10, v10, v14
	v_max_u32_e32 v14, v13, v12
	v_min_u32_e32 v12, v13, v12
	v_max_u32_e32 v13, v8, v9
	v_min_u32_e32 v8, v8, v9
	v_max_u32_e32 v9, v11, v15
	v_min_u32_e32 v11, v11, v15
	v_max_u32_e32 v15, v88, v3
	v_min_u32_e32 v3, v88, v3
	v_max_u32_e32 v88, v5, v7
	v_min_u32_e32 v5, v5, v7
	v_max_u32_e32 v7, v4, v2
	v_min_u32_e32 v2, v4, v2
	v_max_u32_e32 v4, v1, v0
	v_min_u32_e32 v0, v1, v0
	v_min_u32_e32 v49, v54, v62
	v_min_u32_e32 v65, v58, v60
	v_min_u32_e32 v66, v61, v57
	v_min_u32_e32 v67, v56, v59
	v_min_u32_e32 v68, v63, v64
	v_min_u32_e32 v69, v51, v53
	v_min_u32_e32 v70, v55, v52
	v_min_u32_e32 v71, v50, v48
	v_min_u32_e32 v33, v38, v46
	v_min_u32_e32 v73, v42, v44
	v_min_u32_e32 v74, v45, v41
	v_min_u32_e32 v75, v40, v43
	v_min_u32_e32 v76, v47, v72
	v_min_u32_e32 v77, v35, v37
	v_min_u32_e32 v78, v39, v36
	v_min_u32_e32 v79, v34, v32
	v_min_u32_e32 v17, v22, v30
	v_min_u32_e32 v81, v26, v28
	v_min_u32_e32 v82, v29, v25
	v_min_u32_e32 v83, v24, v27
	v_min_u32_e32 v84, v31, v80
	v_min_u32_e32 v85, v19, v21
	v_min_u32_e32 v86, v23, v20
	v_min_u32_e32 v87, v18, v16
	v_min_u32_e32 v1, v6, v14
	v_min_u32_e32 v89, v10, v12
	v_min_u32_e32 v90, v13, v9
	v_min_u32_e32 v91, v8, v11
	v_min_u32_e32 v92, v15, v88
	v_min_u32_e32 v93, v3, v5
	v_min_u32_e32 v94, v7, v4
	v_min_u32_e32 v95, v2, v0
	v_max3_u32 v54, v54, v62, v79
	v_max3_u32 v32, v49, v34, v32
	v_max3_u32 v34, v58, v60, v78
	v_max3_u32 v36, v65, v39, v36
	v_max3_u32 v39, v61, v57, v77
	v_max3_u32 v35, v66, v35, v37
	v_max3_u32 v37, v56, v59, v76
	v_max3_u32 v47, v67, v47, v72
	v_max3_u32 v49, v63, v64, v75
	v_max3_u32 v40, v68, v40, v43
	v_max3_u32 v43, v51, v53, v74
	v_max3_u32 v41, v69, v45, v41
	v_max3_u32 v45, v55, v52, v73
	v_max3_u32 v42, v70, v42, v44
	v_max3_u32 v33, v50, v48, v33
	v_max3_u32 v38, v71, v38, v46
	v_max3_u32 v22, v22, v30, v95
	v_max3_u32 v0, v17, v2, v0
	v_max3_u32 v2, v26, v28, v94
	v_max3_u32 v4, v81, v7, v4
	v_max3_u32 v7, v29, v25, v93
	v_max3_u32 v3, v82, v3, v5
	v_max3_u32 v5, v24, v27, v92
	v_max3_u32 v15, v83, v15, v88
	v_max3_u32 v17, v31, v80, v91
	v_max3_u32 v8, v84, v8, v11
	v_max3_u32 v11, v19, v21, v90
	v_max3_u32 v9, v85, v13, v9
	v_max3_u32 v13, v23, v20, v89
	v_max3_u32 v10, v86, v10, v12
	v_max3_u32 v1, v18, v16, v1
	v_max3_u32 v6, v87, v6, v14
	v_max_u32_e32 v44, v54, v49
	v_min_u32_e32 v46, v54, v49
	v_max_u32_e32 v48, v32, v40
	v_min_u32_e32 v32, v32, v40
	v_max_u32_e32 v40, v34, v43
	v_min_u32_e32 v34, v34, v43
	v_max_u32_e32 v43, v36, v41
	v_min_u32_e32 v36, v36, v41
	v_max_u32_e32 v41, v39, v45
	v_min_u32_e32 v39, v39, v45
	v_max_u32_e32 v45, v35, v42
	v_min_u32_e32 v35, v35, v42
	v_max_u32_e32 v42, v37, v33
	v_min_u32_e32 v33, v37, v33
	v_max_u32_e32 v37, v47, v38
	v_min_u32_e32 v38, v47, v38
	v_max_u32_e32 v12, v22, v17
	v_min_u32_e32 v14, v22, v17
	v_max_u32_e32 v16, v0, v8
	v_min_u32_e32 v0, v0, v8
	v_max_u32_e32 v8, v2, v11
	v_min_u32_e32 v2, v2, v11
	v_max_u32_e32 v11, v4, v9
	v_min_u32_e32 v4, v4, v9
	v_max_u32_e32 v9, v7, v13
	v_min_u32_e32 v7, v7, v13
	v_max_u32_e32 v13, v3, v10
	v_min_u32_e32 v3, v3, v10
	v_max_u32_e32 v10, v5, v1
	v_min_u32_e32 v1, v5, v1
	v_max_u32_e32 v5, v15, v6
	v_min_u32_e32 v6, v15, v6
	v_max_u32_e32 v47, v44, v41
	v_min_u32_e32 v41, v44, v41
	v_max_u32_e32 v44, v48, v45
	v_min_u32_e32 v45, v48, v45
	v_max_u32_e32 v48, v40, v42
	v_min_u32_e32 v40, v40, v42
	v_max_u32_e32 v42, v43, v37
	v_min_u32_e32 v37, v43, v37
	v_max_u32_e32 v43, v46, v39
	v_min_u32_e32 v39, v46, v39
	v_max_u32_e32 v46, v32, v35
	v_min_u32_e32 v32, v32, v35
	v_max_u32_e32 v35, v34, v33
	v_min_u32_e32 v33, v34, v33
	v_max_u32_e32 v34, v36, v38
	v_min_u32_e32 v36, v36, v38
	v_max_u32_e32 v15, v12, v9
	v_min_u32_e32 v9, v12, v9
	v_max_u32_e32 v12, v16, v13
	v_min_u32_e32 v13, v16, v13
	v_max_u32_e32 v16, v8, v10
	v_min_u32_e32 v8, v8, v10
	v_max_u32_e32 v10, v11, v5
	v_min_u32_e32 v5, v11, v5
	v_max_u32_e32 v11, v14, v7
	v_min_u32_e32 v7, v14, v7
	v_max_u32_e32 v14, v0, v3
	v_min_u32_e32 v0, v0, v3
	v_max_u32_e32 v3, v2, v1
	v_min_u32_e32 v1, v2, v1
	v_max_u32_e32 v2, v4, v6
	v_min_u32_e32 v4, v4, v6
	v_max_u32_e32 v38, v47, v48
	v_min_u32_e32 v47, v47, v48
	v_max_u32_e32 v48, v44, v42
	v_min_u32_e32 v42, v44, v42
	v_max_u32_e32 v44, v41, v40
	v_min_u32_e32 v40, v41, v40
	v_max_u32_e32 v41, v45, v37
	v_min_u32_e32 v37, v45, v37
	v_max_u32_e32 v45, v43, v35
	v_min_u32_e32 v35, v43, v35
	v_max_u32_e32 v43, v46, v34
	v_min_u32_e32 v34, v46, v34
	v_max_u32_e32 v46, v39, v33
	v_min_u32_e32 v33, v39, v33
	v_max_u32_e32 v39, v32, v36
; DEV unsigned xor32_u(unsigned v) { return (unsigned)__shfl_xor((int)v, 32, 64); }
; __device__ void peer_q_topk_item(const Params& P, int l, int item, char* smem) {
;     ...
;       merge_top16(Lc, G1); merge_top16(G2, G3); merge_top16(Lc, G2);
;     }
;     {
;       unsigned oth[16];
; #pragma unroll
;       for (int i = 0; i < 16; ++i) oth[i] = xor32_u(Lc[i]);
;       merge_top16(Lc, oth);
;     }
; #pragma unroll
;     for (int i = 0; i < 16; ++i) { L0[i] = L1[i]; L1[i] = Lc[i]; }
	v_min_u32_e32 v32, v32, v36
	v_max_u32_e32 v6, v15, v16
	v_min_u32_e32 v15, v15, v16
	v_max_u32_e32 v16, v12, v10
	v_min_u32_e32 v10, v12, v10
	v_max_u32_e32 v12, v9, v8
	v_min_u32_e32 v8, v9, v8
	v_max_u32_e32 v9, v13, v5
	v_min_u32_e32 v5, v13, v5
	v_max_u32_e32 v13, v11, v3
	v_min_u32_e32 v3, v11, v3
	v_max_u32_e32 v11, v14, v2
	v_min_u32_e32 v2, v14, v2
	v_max_u32_e32 v14, v7, v1
	v_min_u32_e32 v1, v7, v1
	v_max_u32_e32 v7, v0, v4
	v_min_u32_e32 v0, v0, v4
	v_min_u32_e32 v36, v38, v48
	v_min_u32_e32 v49, v47, v42
	v_min_u32_e32 v50, v44, v41
	v_min_u32_e32 v51, v40, v37
	v_min_u32_e32 v52, v45, v43
	v_min_u32_e32 v53, v35, v34
	v_min_u32_e32 v54, v46, v39
	v_min_u32_e32 v55, v33, v32
	v_min_u32_e32 v4, v6, v16
	v_min_u32_e32 v17, v15, v10
	v_min_u32_e32 v18, v12, v9
	v_min_u32_e32 v19, v8, v5
	v_min_u32_e32 v20, v13, v11
	v_min_u32_e32 v21, v3, v2
	v_min_u32_e32 v22, v14, v7
	v_min_u32_e32 v23, v1, v0
	v_max3_u32 v23, v38, v48, v23
	v_max3_u32 v0, v36, v1, v0
	v_max3_u32 v1, v47, v42, v22
	v_max3_u32 v7, v49, v14, v7
	v_max3_u32 v14, v44, v41, v21
	v_max3_u32 v2, v50, v3, v2
	v_max3_u32 v3, v40, v37, v20
	v_max3_u32 v11, v51, v13, v11
	v_max3_u32 v13, v45, v43, v19
	v_max3_u32 v5, v52, v8, v5
	v_max3_u32 v8, v35, v34, v18
	v_max3_u32 v9, v53, v12, v9
	v_max3_u32 v12, v46, v39, v17
	v_max3_u32 v10, v54, v15, v10
	v_max3_u32 v4, v33, v32, v4
	v_max3_u32 v6, v55, v6, v16
	v_max_u32_e32 v15, v23, v13
	v_min_u32_e32 v13, v23, v13
	v_max_u32_e32 v16, v0, v5
	v_min_u32_e32 v0, v0, v5
	v_max_u32_e32 v5, v1, v8
	v_min_u32_e32 v1, v1, v8
	v_max_u32_e32 v8, v7, v9
	v_min_u32_e32 v7, v7, v9
	v_max_u32_e32 v9, v14, v12
	v_min_u32_e32 v12, v14, v12
	v_max_u32_e32 v14, v2, v10
	v_min_u32_e32 v2, v2, v10
	v_max_u32_e32 v10, v3, v4
	v_min_u32_e32 v3, v3, v4
	v_max_u32_e32 v4, v11, v6
	v_min_u32_e32 v6, v11, v6
	v_max_u32_e32 v11, v15, v9
	v_min_u32_e32 v9, v15, v9
	v_max_u32_e32 v15, v16, v14
	v_min_u32_e32 v14, v16, v14
	v_max_u32_e32 v16, v5, v10
	v_min_u32_e32 v5, v5, v10
	v_max_u32_e32 v10, v8, v4
	v_min_u32_e32 v4, v8, v4
	v_max_u32_e32 v8, v13, v12
	v_min_u32_e32 v12, v13, v12
	v_max_u32_e32 v13, v0, v2
	v_min_u32_e32 v0, v0, v2
	v_max_u32_e32 v2, v1, v3
	v_min_u32_e32 v1, v1, v3
	v_max_u32_e32 v3, v7, v6
	v_min_u32_e32 v6, v7, v6
	v_max_u32_e32 v7, v11, v16
	v_min_u32_e32 v11, v11, v16
	v_max_u32_e32 v16, v15, v10
	v_min_u32_e32 v10, v15, v10
	v_max_u32_e32 v15, v9, v5
	v_min_u32_e32 v5, v9, v5
	v_max_u32_e32 v9, v14, v4
	v_min_u32_e32 v4, v14, v4
	v_max_u32_e32 v14, v8, v2
	v_min_u32_e32 v2, v8, v2
	v_max_u32_e32 v8, v13, v3
	v_min_u32_e32 v3, v13, v3
	v_max_u32_e32 v13, v12, v1
	v_min_u32_e32 v1, v12, v1
	v_max_u32_e32 v12, v0, v6
	v_min_u32_e32 v0, v0, v6
	v_max_u32_e32 v6, v7, v16
	v_min_u32_e32 v7, v7, v16
	v_max_u32_e32 v16, v11, v10
	v_min_u32_e32 v10, v11, v10
	v_max_u32_e32 v11, v15, v9
	v_min_u32_e32 v9, v15, v9
	v_max_u32_e32 v15, v5, v4
	v_min_u32_e32 v4, v5, v4
	v_max_u32_e32 v5, v14, v8
	v_min_u32_e32 v8, v14, v8
	v_max_u32_e32 v14, v2, v3
	v_min_u32_e32 v2, v2, v3
	v_max_u32_e32 v3, v13, v12
	v_min_u32_e32 v12, v13, v12
	v_max_u32_e32 v13, v1, v0
	v_min_u32_e32 v0, v1, v0
	ds_bpermute_b32 v1, v162, v6
	ds_bpermute_b32 v17, v162, v7
	ds_bpermute_b32 v18, v162, v16
	ds_bpermute_b32 v19, v162, v10
	ds_bpermute_b32 v20, v162, v11
	ds_bpermute_b32 v21, v162, v9
	ds_bpermute_b32 v22, v162, v15
	ds_bpermute_b32 v23, v162, v4
	ds_bpermute_b32 v24, v162, v5
	ds_bpermute_b32 v25, v162, v8
	ds_bpermute_b32 v26, v162, v14
	ds_bpermute_b32 v27, v162, v2
	ds_bpermute_b32 v28, v162, v3
	ds_bpermute_b32 v29, v162, v12
	ds_bpermute_b32 v30, v162, v13
	ds_bpermute_b32 v31, v162, v0
	s_waitcnt lgkmcnt(4)
	v_max_u32_e32 v11, v11, v27
	s_waitcnt lgkmcnt(3)
	v_max_u32_e32 v10, v10, v28
	s_waitcnt lgkmcnt(2)
	v_max_u32_e32 v16, v16, v29
	s_waitcnt lgkmcnt(1)
	v_max_u32_e32 v7, v7, v30
	s_waitcnt lgkmcnt(0)
	v_max_u32_e32 v6, v6, v31
	v_max_u32_e32 v9, v9, v26
	v_max_u32_e32 v15, v15, v25
	v_max_u32_e32 v4, v4, v24
	v_max_u32_e32 v5, v5, v23
	v_max_u32_e32 v8, v8, v22
	v_max_u32_e32 v14, v14, v21
	v_max_u32_e32 v2, v2, v20
	v_max_u32_e32 v3, v3, v19
	v_max_u32_e32 v12, v12, v18
	v_max_u32_e32 v13, v13, v17
	v_max_u32_e32 v0, v0, v1
	v_max_u32_e32 v1, v6, v5
	v_min_u32_e32 v5, v6, v5
	v_max_u32_e32 v6, v7, v8
	v_min_u32_e32 v7, v7, v8
	v_max_u32_e32 v8, v16, v14
	v_min_u32_e32 v14, v16, v14
	v_max_u32_e32 v16, v10, v2
	v_min_u32_e32 v2, v10, v2
	v_max_u32_e32 v10, v11, v3
	v_min_u32_e32 v3, v11, v3
	v_max_u32_e32 v11, v9, v12
	v_min_u32_e32 v9, v9, v12
	v_max_u32_e32 v12, v15, v13
	v_min_u32_e32 v13, v15, v13
	v_max_u32_e32 v15, v4, v0
	v_min_u32_e32 v0, v4, v0
	v_max_u32_e32 v4, v1, v10
	v_min_u32_e32 v1, v1, v10
	v_max_u32_e32 v10, v6, v11
	v_min_u32_e32 v6, v6, v11
	v_max_u32_e32 v11, v8, v12
	v_min_u32_e32 v8, v8, v12
	v_max_u32_e32 v12, v16, v15
	v_min_u32_e32 v15, v16, v15
	v_max_u32_e32 v16, v5, v3
	v_min_u32_e32 v3, v5, v3
	v_max_u32_e32 v5, v7, v9
	v_min_u32_e32 v7, v7, v9
	v_max_u32_e32 v9, v14, v13
	v_min_u32_e32 v13, v14, v13
	v_max_u32_e32 v14, v2, v0
	v_min_u32_e32 v0, v2, v0
	v_max_u32_e32 v2, v4, v11
	v_min_u32_e32 v4, v4, v11
	v_max_u32_e32 v11, v10, v12
	v_min_u32_e32 v10, v10, v12
	v_max_u32_e32 v12, v1, v8
	v_min_u32_e32 v8, v1, v8
	v_max_u32_e32 v17, v6, v15
	v_min_u32_e32 v6, v6, v15
	v_max_u32_e32 v15, v16, v9
	v_min_u32_e32 v9, v16, v9
	v_max_u32_e32 v18, v5, v14
	v_min_u32_e32 v5, v5, v14
	v_max_u32_e32 v19, v3, v13
	v_min_u32_e32 v20, v3, v13
	v_max_u32_e32 v21, v7, v0
	v_min_u32_e32 v22, v7, v0
	v_max_u32_e32 v16, v2, v11
	v_min_u32_e32 v3, v2, v11
	v_max_u32_e32 v0, v4, v10
	v_min_u32_e32 v10, v4, v10
	v_max_u32_e32 v1, v12, v17
	v_min_u32_e32 v11, v12, v17
	v_max_u32_e32 v12, v8, v6
	v_min_u32_e32 v13, v8, v6
	v_max_u32_e32 v14, v15, v18
	v_min_u32_e32 v2, v15, v18
	v_max_u32_e32 v7, v9, v5
	v_min_u32_e32 v4, v9, v5
	v_max_u32_e32 v8, v19, v21
	v_min_u32_e32 v5, v19, v21
	v_max_u32_e32 v15, v20, v22
	v_min_u32_e32 v6, v20, v22
	s_mov_b64 s[38:39], 0
	s_and_b64 vcc, exec, s[0:1]
	s_cbranch_vccnz .LBB0_49
	v_mov_b32_e32 v119, v15
	v_mov_b32_e32 v115, v6
	v_mov_b32_e32 v101, v14
	v_mov_b32_e32 v103, v2
	v_mov_b32_e32 v96, v4
	v_mov_b32_e32 v97, v7
	v_mov_b32_e32 v107, v8
	v_mov_b32_e32 v111, v5
	v_mov_b32_e32 v158, v16
	v_mov_b32_e32 v168, v3
	v_mov_b32_e32 v165, v0
	v_mov_b32_e32 v155, v10
	v_mov_b32_e32 v123, v1
	v_mov_b32_e32 v131, v11
	v_mov_b32_e32 v135, v12
	v_mov_b32_e32 v127, v13
	s_branch .LBB0_45
